# 4-WG seams for GEMM-GEMM hand-offs + full-128B-line EpiResid epilogues (lane-pair exchange) for P2/P7/P10
# speedup vs baseline: 1.0189x; 1.0189x over previous
; #define LAS __attribute__((address_space(3)))
; __device__ __forceinline__ unsigned xb_add(unsigned* p, unsigned v) { return __hip_atomic_fetch_add(p, v, __ATOMIC_RELAXED, __HIP_MEMORY_SCOPE_AGENT); }
; __device__ __forceinline__ unsigned xb_xcc_id() { return (unsigned)__builtin_amdgcn_s_getreg((3 << 11) | 20) & 0xFu; }
; __device__ __forceinline__ XcdBarrier xcd_barrier_post(unsigned* bar, volatile LAS unsigned* st) {
;     XcdBarrier b; b.bar = bar; b.x = xb_xcc_id(); b.st = st;
;     if (threadIdx.x == 0) (void)xb_add(&bar[XB_XCNT(b.x)], 1u);
;     return b;
; }
; __global__ void __launch_bounds__(NWAVES * 64, 2) hybrid_fwd(Args args) {
;     ...
;     const int tid = threadIdx.x, lane = tid & 63, wave = __builtin_amdgcn_readfirstlane(tid >> 6);
;     const int G = gridDim.x, gw = blockIdx.x * NWAVES + wave, ngw = G * NWAVES;
;     unsigned char* ws = args.ws;
;     const int lo = args.ph_lo, hi = args.ph_hi;
;     ...
;     if (tid < 64) ((LAS unsigned*)(lds + MISC_OFF))[tid] = 0u;
;     __syncthreads();
;     XcdBarrier bar; bar.bar = (unsigned*)(ws + WS_BAR); bar.x = 0; bar.st = (volatile LAS unsigned*)(lds + MISC_OFF + 32);
;     if (hi - lo > 1) bar = xcd_barrier_post((unsigned*)(ws + WS_BAR), (volatile LAS unsigned*)(lds + MISC_OFF + 32));
_Z10hybrid_fwd4Args:
	s_mov_b32 s66, s2
	s_load_dwordx16 s[76:91], s[0:1], 0x80
	s_load_dwordx2 s[2:3], s[0:1], 0xc0
	v_and_b32_e32 v189, 0x3ff, v0
	v_cmp_gt_u32_e32 vcc, 64, v189
	v_readfirstlane_b32 s20, v189
	s_waitcnt lgkmcnt(0)
	v_writelane_b32 v254, s2, 0
	s_nop 1
	v_writelane_b32 v254, s3, 1
	s_add_u32 s2, s0, 0xc8
	s_addc_u32 s3, s1, 0
	v_writelane_b32 v254, s2, 2
	s_nop 1
	v_writelane_b32 v254, s3, 3
	s_and_saveexec_b64 s[4:5], vcc
	v_lshl_add_u32 v1, v189, 2, 0
	v_add_u32_e32 v1, 0x20400, v1
	v_mov_b32_e32 v2, 0
	ds_write_b32 v1, v2
	s_or_b64 exec, exec, s[4:5]
	s_add_u32 s2, s90, 0x2c0000
	s_addc_u32 s3, s91, 0
	v_writelane_b32 v254, s2, 4
	s_load_dword s67, s[0:1], 0xc8
	v_cmp_eq_u32_e32 vcc, 0, v189
	v_writelane_b32 v254, s3, 5
	s_load_dwordx2 s[2:3], s[0:1], 0xc0
	s_waitcnt lgkmcnt(0)
	s_barrier
	s_sub_i32 s2, s3, s2
	s_mov_b32 s3, 0
	v_writelane_b32 v254, s3, 6
	s_cmp_lt_i32 s2, 2
	s_cbranch_scc1 .LBB0_7
	s_getreg_b32 s2, hwreg(HW_REG_XCC_ID, 0, 4)
	s_and_b32 s2, s2, 15
	v_writelane_b32 v254, s2, 6
	s_and_saveexec_b64 s[4:5], vcc
	s_cbranch_execz .LBB0_6
	s_mov_b64 s[6:7], exec
	v_mbcnt_lo_u32_b32 v1, s6, 0
	v_mbcnt_hi_u32_b32 v1, s7, v1
	v_cmp_eq_u32_e32 vcc, 0, v1
	s_and_b64 s[2:3], exec, vcc
	s_mov_b64 exec, s[2:3]
	s_cbranch_execz .LBB0_6
	v_readlane_b32 s2, v254, 6
	s_lshl_b32 s2, s2, 8
	s_bcnt1_i32_b64 s3, s[6:7]
	v_mov_b32_e32 v1, s2
	v_mov_b32_e32 v2, s3
	v_readlane_b32 s2, v254, 4
	v_readlane_b32 s3, v254, 5
	s_nop 4
	global_atomic_add v1, v2, s[2:3] offset:1024
	v_readlane_b32 s6, v254, 6
	s_and_b32 s7, s66, 63
	s_lshl_b32 s6, 1, s6
	s_lshl_b32 s7, s7, 2
	v_mov_b32_e32 v3, s7
	v_mov_b32_e32 v4, s6
	global_atomic_or v3, v4, s[2:3]

; #define LAS __attribute__((address_space(3)))
; __global__ void __launch_bounds__(NWAVES * 64, 2) hybrid_fwd(Args args) {
;     ...
;     if (hi - lo > 1) bar = xcd_barrier_post((unsigned*)(ws + WS_BAR), (volatile LAS unsigned*)(lds + MISC_OFF + 32));
;     ...
;     if (lo < 0) cg::this_grid().sync();
.LBB0_105:
	s_or_b64 exec, exec, s[4:5]
	s_waitcnt lgkmcnt(0)
	s_barrier
	v_readlane_b32 s2, v254, 4
	v_readlane_b32 s3, v254, 5
	v_lshlrev_b32_e32 v0, 2, v188
	s_nop 4
	global_load_dword v1, v0, s[2:3] sc1
	s_waitcnt vmcnt(0)
	v_add_u32_e32 v2, -1, v1
	v_and_b32_e32 v2, v2, v1
	v_cmp_eq_u32_e32 vcc, 0, v2
	v_cmp_ne_u32_e64 s[4:5], 0, v1
	s_and_b64 s[4:5], vcc, s[4:5]
	s_cmp_eq_u64 s[4:5], exec
	s_cselect_b32 s2, 1, 0
	v_mov_b32_e32 v0, s2
	v_mov_b32_e32 v1, 0x20430
	ds_write_b32 v1, v0

; __device__ __forceinline__ unsigned xb_ld(unsigned* p)              { return __hip_atomic_load(p, __ATOMIC_RELAXED, __HIP_MEMORY_SCOPE_AGENT); }
; __device__ __forceinline__ unsigned xb_add(unsigned* p, unsigned v) { return __hip_atomic_fetch_add(p, v, __ATOMIC_RELAXED, __HIP_MEMORY_SCOPE_AGENT); }
; __device__ __forceinline__ void xcd_barrier_complete(unsigned* bar, unsigned x, unsigned& nloc, unsigned& nx) {
;     const unsigned G = gridDim.x * gridDim.y * gridDim.z;
;     unsigned sum, cnt, mine, sp = 0u;
;     for (;;) {
;         sum = 0u; cnt = 0u; mine = 0u;
; #pragma unroll
;         for (unsigned j = 0; j < 16; ++j) { const unsigned c = xb_ld(&bar[XB_XCNT(j)]); sum += c; cnt += (c > 0u) ? 1u : 0u; mine = (j == x) ? c : mine; }
;         if (sum == G) break;
; __device__ __forceinline__ void xcd_barrier(const XcdBarrier& b) {
;     asm volatile("s_waitcnt vmcnt(0)" ::: "memory");
;     __syncthreads();
;     if (threadIdx.x == 0) {
;         unsigned* bar = b.bar;
;         __builtin_amdgcn_s_waitcnt(0);
;         unsigned nloc = b.st[0], nx = b.st[1];
;         if (nloc == 0u) { xcd_barrier_complete(bar, b.x, nloc, nx); b.st[0] = nloc; b.st[1] = nx; }
;         const unsigned old = xb_add(&bar[XB_XSUB(b.x)], 1u);
.LBB0_123:
	v_readlane_b32 s0, v254, 0
	v_readlane_b32 s1, v254, 1
	s_cmp_gt_i32 s1, 2
	s_cselect_b64 s[0:1], -1, 0
	s_and_b64 s[2:3], s[4:5], s[0:1]
	s_andn2_b64 vcc, exec, s[2:3]
	s_cbranch_vccnz .LBB0_173
	s_waitcnt vmcnt(0)
	v_cmp_eq_u32_e32 vcc, 0, v189
	s_waitcnt vmcnt(8)
	s_barrier
	s_and_saveexec_b64 s[4:5], vcc
	s_cbranch_execz .LBB0_172
	v_mov_b32_e32 v0, 0x20430
	ds_read_b32 v0, v0
	s_waitcnt lgkmcnt(0)
	v_cmp_ne_u32_e32 vcc, 0, v0
	s_cbranch_vccz .Lseam_slow_1
	v_readlane_b32 s8, v255, 0
	v_readlane_b32 s2, v254, 4
	v_readlane_b32 s3, v254, 5
	s_and_b32 s8, s8, 63
	s_lshl_b32 s8, s8, 2
	s_add_i32 s8, s8, 0x100
	v_mov_b32_e32 v0, s8
	v_mov_b32_e32 v1, 1
	s_mov_b32 s9, 0
	s_nop 2
	global_atomic_add v0, v1, s[2:3]
.Lseam_spin_1:
	global_load_dword v2, v0, s[2:3] sc1
	s_add_i32 s9, s9, 1
	s_waitcnt vmcnt(0)
	v_cmp_gt_u32_e32 vcc, 4, v2
	s_cbranch_vccz .Lseam_done_1
	s_cmp_gt_u32 s9, 30000
	s_cbranch_scc1 .Lseam_done_1
	s_sleep 1
	s_branch .Lseam_spin_1
.Lseam_done_1:
	buffer_inv sc1
	s_waitcnt vmcnt(0)
	s_branch .LBB0_172
.Lseam_slow_1:
	s_add_i32 s2, 0, 0x20420
	v_mov_b32_e32 v0, s2
	s_waitcnt vmcnt(0) expcnt(0) lgkmcnt(0)
	ds_read_b32 v2, v0
	s_add_i32 s2, 0, 0x20424
	v_mov_b32_e32 v0, s2
	ds_read_b32 v0, v0
	s_waitcnt lgkmcnt(1)
	v_cmp_ne_u32_e32 vcc, 0, v2
	s_cbranch_vccnz .LBB0_140
	v_readlane_b32 s6, v254, 2
	v_readlane_b32 s7, v254, 3
	s_load_dwordx2 s[2:3], s[6:7], 0x4
	s_add_u32 s6, s90, 0x2c0200
	s_addc_u32 s7, s91, 0
	s_add_u32 s26, s90, 0x2c0400
	s_addc_u32 s27, s91, 0
	s_add_u32 s30, s90, 0x2c0500
	s_addc_u32 s31, s91, 0
	s_add_u32 s38, s90, 0x2c0600
	s_addc_u32 s39, s91, 0
	s_add_u32 s42, s90, 0x2c0700
	s_addc_u32 s43, s91, 0
	s_add_u32 s44, s90, 0x2c0800
	s_addc_u32 s45, s91, 0
	s_add_u32 s46, s90, 0x2c0900
	s_addc_u32 s47, s91, 0
	s_add_u32 s56, s90, 0x2c0a00
	s_addc_u32 s57, s91, 0
	s_add_u32 s64, s90, 0x2c0b00
	s_addc_u32 s65, s91, 0
	s_add_u32 s72, s90, 0x2c0c00
	s_addc_u32 s73, s91, 0
	s_add_u32 s74, s90, 0x2c0d00
	s_addc_u32 s75, s91, 0
	s_add_u32 s80, s90, 0x2c0e00
	s_addc_u32 s81, s91, 0
	s_add_u32 s82, s90, 0x2c0f00
	s_addc_u32 s83, s91, 0
	s_add_u32 s84, s90, 0x2c1000
	s_addc_u32 s85, s91, 0
	s_add_u32 s86, s90, 0x2c1100
	s_addc_u32 s87, s91, 0
	s_add_u32 s88, s90, 0x2c1200
	s_addc_u32 s89, s91, 0
	s_waitcnt lgkmcnt(0)
	s_mul_i32 s2, s2, s67
	s_add_u32 s90, s90, 0x2c1300
	s_mul_i32 s2, s2, s3
	s_addc_u32 s91, s91, 0
	s_mov_b32 s3, 1
	v_mov_b32_e32 v16, 0
	s_branch .LBB0_128

;     __device__ __forceinline__ void operator()(const f32x4 (&acc)[2][2][4][2], const Unit& u, int wr, int wc, int fr, int fq) const {
;         int row0 = u.pm * BM + wr * 64 + fr, col0 = u.pn * BM + wc * 32 + 4 * fq;
;         asm volatile("" : "+v"(row0), "+v"(col0));
;         f32x4 b[2][2][2][2];
; #pragma unroll
;         for (int ch = 0; ch <= 4; ++ch) {
;             if (ch < 4) {
; #pragma unroll
;                 for (int mm = 0; mm < 2; ++mm) { const size_t off = (size_t)(row0 + (ch >> 1) * HALF + ((ch & 1) * 2 + mm) * 16) * ldc + col0;
; #pragma unroll
;                     for (int bj = 0; bj < 2; ++bj)
; #pragma unroll
;                         for (int n = 0; n < 2; ++n) b[ch & 1][mm][bj][n] = *(const f32x4*)(base + off + bj * HALF + n * 16); }
.LBB0_198:
	s_and_b64 vcc, exec, s[0:1]
	v_bfe_u32 v227, v214, 3, 1
	v_and_b32_e32 v228, 0x77, v214
	v_lshl_add_u32 v229, v227, 4, v215
	v_lshl_add_u32 v225, s36, 8, v228
	v_lshl_or_b32 v226, s37, 8, v229
	v_lshlrev_b32_e32 v224, 13, v225
	v_lshl_add_u32 v224, v226, 2, v224
	v_xor_b32_e32 v230, 16, v188
	v_xor_b32_e32 v231, 32, v188
	v_lshlrev_b32_e32 v230, 2, v230
	v_lshlrev_b32_e32 v231, 2, v231
	v_cmp_ne_u32_e64 s[62:63], 0, v227
	v_lshl_add_u32 v232, s36, 8, v214
	v_lshlrev_b32_e32 v232, 7, v232
	v_bfe_u32 v233, v215, 5, 2
	v_lshl_add_u32 v233, s37, 2, v233
	v_lshl_add_u32 v232, v233, 2, v232
	v_lshrrev_b32_e32 v234, 1, v224
	v_readlane_b32 s60, v254, 7
	v_readlane_b32 s61, v254, 8
	v_readlane_b32 s36, v254, 44
	v_readlane_b32 s37, v254, 45
	v_readlane_b32 s48, v255, 10
	v_readlane_b32 s49, v255, 11
	s_nop 7
	v_mov_b32_e32 v132, v144
	v_mov_b32_e32 v133, v145
	v_mov_b32_e32 v134, v146
	v_mov_b32_e32 v135, v147
	v_mov_b32_dpp v144, v160 row_ror:8 row_mask:0xf bank_mask:0x3
	v_mov_b32_dpp v145, v161 row_ror:8 row_mask:0xf bank_mask:0x3
	v_mov_b32_dpp v146, v162 row_ror:8 row_mask:0xf bank_mask:0x3
	v_mov_b32_dpp v147, v163 row_ror:8 row_mask:0xf bank_mask:0x3
	v_mov_b32_dpp v160, v132 row_ror:8 row_mask:0xf bank_mask:0xc
	v_mov_b32_dpp v161, v133 row_ror:8 row_mask:0xf bank_mask:0xc
	v_mov_b32_dpp v162, v134 row_ror:8 row_mask:0xf bank_mask:0xc
	v_mov_b32_dpp v163, v135 row_ror:8 row_mask:0xf bank_mask:0xc
	v_mov_b32_e32 v132, v128
	v_mov_b32_e32 v133, v129
	v_mov_b32_e32 v134, v130
	v_mov_b32_e32 v135, v131
	v_mov_b32_dpp v128, v136 row_ror:8 row_mask:0xf bank_mask:0x3
	v_mov_b32_dpp v129, v137 row_ror:8 row_mask:0xf bank_mask:0x3
	v_mov_b32_dpp v130, v138 row_ror:8 row_mask:0xf bank_mask:0x3
	v_mov_b32_dpp v131, v139 row_ror:8 row_mask:0xf bank_mask:0x3
	v_mov_b32_dpp v136, v132 row_ror:8 row_mask:0xf bank_mask:0xc
	v_mov_b32_dpp v137, v133 row_ror:8 row_mask:0xf bank_mask:0xc
	v_mov_b32_dpp v138, v134 row_ror:8 row_mask:0xf bank_mask:0xc
	v_mov_b32_dpp v139, v135 row_ror:8 row_mask:0xf bank_mask:0xc
	v_mov_b32_e32 v132, v104
	v_mov_b32_e32 v133, v105
	v_mov_b32_e32 v134, v106
	v_mov_b32_e32 v135, v107
	v_mov_b32_dpp v104, v108 row_ror:8 row_mask:0xf bank_mask:0x3
	v_mov_b32_dpp v105, v109 row_ror:8 row_mask:0xf bank_mask:0x3
	v_mov_b32_dpp v106, v110 row_ror:8 row_mask:0xf bank_mask:0x3
	v_mov_b32_dpp v107, v111 row_ror:8 row_mask:0xf bank_mask:0x3
	v_mov_b32_dpp v108, v132 row_ror:8 row_mask:0xf bank_mask:0xc
	v_mov_b32_dpp v109, v133 row_ror:8 row_mask:0xf bank_mask:0xc
	v_mov_b32_dpp v110, v134 row_ror:8 row_mask:0xf bank_mask:0xc
	v_mov_b32_dpp v111, v135 row_ror:8 row_mask:0xf bank_mask:0xc
	v_mov_b32_e32 v132, v96
	v_mov_b32_e32 v133, v97
	v_mov_b32_e32 v134, v98
	v_mov_b32_e32 v135, v99
	v_mov_b32_dpp v96, v100 row_ror:8 row_mask:0xf bank_mask:0x3
	v_mov_b32_dpp v97, v101 row_ror:8 row_mask:0xf bank_mask:0x3
	v_mov_b32_dpp v98, v102 row_ror:8 row_mask:0xf bank_mask:0x3
	v_mov_b32_dpp v99, v103 row_ror:8 row_mask:0xf bank_mask:0x3
	v_mov_b32_dpp v100, v132 row_ror:8 row_mask:0xf bank_mask:0xc
	v_mov_b32_dpp v101, v133 row_ror:8 row_mask:0xf bank_mask:0xc
	v_mov_b32_dpp v102, v134 row_ror:8 row_mask:0xf bank_mask:0xc
	v_mov_b32_dpp v103, v135 row_ror:8 row_mask:0xf bank_mask:0xc
	v_mov_b32_e32 v132, v88
	v_mov_b32_e32 v133, v89
	v_mov_b32_e32 v134, v90
	v_mov_b32_e32 v135, v91
	v_mov_b32_dpp v88, v92 row_ror:8 row_mask:0xf bank_mask:0x3
	v_mov_b32_dpp v89, v93 row_ror:8 row_mask:0xf bank_mask:0x3
	v_mov_b32_dpp v90, v94 row_ror:8 row_mask:0xf bank_mask:0x3
	v_mov_b32_dpp v91, v95 row_ror:8 row_mask:0xf bank_mask:0x3
	v_mov_b32_dpp v92, v132 row_ror:8 row_mask:0xf bank_mask:0xc
	v_mov_b32_dpp v93, v133 row_ror:8 row_mask:0xf bank_mask:0xc
	v_mov_b32_dpp v94, v134 row_ror:8 row_mask:0xf bank_mask:0xc
	v_mov_b32_dpp v95, v135 row_ror:8 row_mask:0xf bank_mask:0xc
	v_mov_b32_e32 v132, v80
	v_mov_b32_e32 v133, v81
	v_mov_b32_e32 v134, v82
	v_mov_b32_e32 v135, v83
	v_mov_b32_dpp v80, v84 row_ror:8 row_mask:0xf bank_mask:0x3
	v_mov_b32_dpp v81, v85 row_ror:8 row_mask:0xf bank_mask:0x3
	v_mov_b32_dpp v82, v86 row_ror:8 row_mask:0xf bank_mask:0x3
	v_mov_b32_dpp v83, v87 row_ror:8 row_mask:0xf bank_mask:0x3
	v_mov_b32_dpp v84, v132 row_ror:8 row_mask:0xf bank_mask:0xc
	v_mov_b32_dpp v85, v133 row_ror:8 row_mask:0xf bank_mask:0xc
	v_mov_b32_dpp v86, v134 row_ror:8 row_mask:0xf bank_mask:0xc
	v_mov_b32_dpp v87, v135 row_ror:8 row_mask:0xf bank_mask:0xc
	v_mov_b32_e32 v132, v72
	v_mov_b32_e32 v133, v73
	v_mov_b32_e32 v134, v74
	v_mov_b32_e32 v135, v75
	v_mov_b32_dpp v72, v76 row_ror:8 row_mask:0xf bank_mask:0x3
	v_mov_b32_dpp v73, v77 row_ror:8 row_mask:0xf bank_mask:0x3
	v_mov_b32_dpp v74, v78 row_ror:8 row_mask:0xf bank_mask:0x3
	v_mov_b32_dpp v75, v79 row_ror:8 row_mask:0xf bank_mask:0x3
	v_mov_b32_dpp v76, v132 row_ror:8 row_mask:0xf bank_mask:0xc
	v_mov_b32_dpp v77, v133 row_ror:8 row_mask:0xf bank_mask:0xc
	v_mov_b32_dpp v78, v134 row_ror:8 row_mask:0xf bank_mask:0xc
	v_mov_b32_dpp v79, v135 row_ror:8 row_mask:0xf bank_mask:0xc
	v_mov_b32_e32 v132, v64
	v_mov_b32_e32 v133, v65
	v_mov_b32_e32 v134, v66
	v_mov_b32_e32 v135, v67
	v_mov_b32_dpp v64, v68 row_ror:8 row_mask:0xf bank_mask:0x3
	v_mov_b32_dpp v65, v69 row_ror:8 row_mask:0xf bank_mask:0x3
	v_mov_b32_dpp v66, v70 row_ror:8 row_mask:0xf bank_mask:0x3
	v_mov_b32_dpp v67, v71 row_ror:8 row_mask:0xf bank_mask:0x3
	v_mov_b32_dpp v68, v132 row_ror:8 row_mask:0xf bank_mask:0xc
	v_mov_b32_dpp v69, v133 row_ror:8 row_mask:0xf bank_mask:0xc
	v_mov_b32_dpp v70, v134 row_ror:8 row_mask:0xf bank_mask:0xc
	v_mov_b32_dpp v71, v135 row_ror:8 row_mask:0xf bank_mask:0xc
	v_mov_b32_e32 v132, v56
;     __device__ __forceinline__ void operator()(const f32x4 (&acc)[2][2][4][2], const Unit& u, int wr, int wc, int fr, int fq) const {
;     ...
;         for (int ch = 0; ch <= 4; ++ch) {
;             if (ch < 4) {
; #pragma unroll
;                 for (int mm = 0; mm < 2; ++mm) { const size_t off = (size_t)(row0 + (ch >> 1) * HALF + ((ch & 1) * 2 + mm) * 16) * ldc + col0;
; #pragma unroll
;                     for (int bj = 0; bj < 2; ++bj)
; #pragma unroll
;                         for (int n = 0; n < 2; ++n) b[ch & 1][mm][bj][n] = *(const f32x4*)(base + off + bj * HALF + n * 16); }
	v_mov_b32_e32 v133, v57
	v_mov_b32_e32 v134, v58
	v_mov_b32_e32 v135, v59
	v_mov_b32_dpp v56, v60 row_ror:8 row_mask:0xf bank_mask:0x3
	v_mov_b32_dpp v57, v61 row_ror:8 row_mask:0xf bank_mask:0x3
	v_mov_b32_dpp v58, v62 row_ror:8 row_mask:0xf bank_mask:0x3
	v_mov_b32_dpp v59, v63 row_ror:8 row_mask:0xf bank_mask:0x3
	v_mov_b32_dpp v60, v132 row_ror:8 row_mask:0xf bank_mask:0xc
	v_mov_b32_dpp v61, v133 row_ror:8 row_mask:0xf bank_mask:0xc
	v_mov_b32_dpp v62, v134 row_ror:8 row_mask:0xf bank_mask:0xc
	v_mov_b32_dpp v63, v135 row_ror:8 row_mask:0xf bank_mask:0xc
	v_mov_b32_e32 v132, v48
	v_mov_b32_e32 v133, v49
	v_mov_b32_e32 v134, v50
	v_mov_b32_e32 v135, v51
	v_mov_b32_dpp v48, v52 row_ror:8 row_mask:0xf bank_mask:0x3
	v_mov_b32_dpp v49, v53 row_ror:8 row_mask:0xf bank_mask:0x3
	v_mov_b32_dpp v50, v54 row_ror:8 row_mask:0xf bank_mask:0x3
	v_mov_b32_dpp v51, v55 row_ror:8 row_mask:0xf bank_mask:0x3
	v_mov_b32_dpp v52, v132 row_ror:8 row_mask:0xf bank_mask:0xc
	v_mov_b32_dpp v53, v133 row_ror:8 row_mask:0xf bank_mask:0xc
	v_mov_b32_dpp v54, v134 row_ror:8 row_mask:0xf bank_mask:0xc
	v_mov_b32_dpp v55, v135 row_ror:8 row_mask:0xf bank_mask:0xc
	v_mov_b32_e32 v132, v40
	v_mov_b32_e32 v133, v41
	v_mov_b32_e32 v134, v42
	v_mov_b32_e32 v135, v43
	v_mov_b32_dpp v40, v44 row_ror:8 row_mask:0xf bank_mask:0x3
	v_mov_b32_dpp v41, v45 row_ror:8 row_mask:0xf bank_mask:0x3
	v_mov_b32_dpp v42, v46 row_ror:8 row_mask:0xf bank_mask:0x3
	v_mov_b32_dpp v43, v47 row_ror:8 row_mask:0xf bank_mask:0x3
	v_mov_b32_dpp v44, v132 row_ror:8 row_mask:0xf bank_mask:0xc
	v_mov_b32_dpp v45, v133 row_ror:8 row_mask:0xf bank_mask:0xc
	v_mov_b32_dpp v46, v134 row_ror:8 row_mask:0xf bank_mask:0xc
	v_mov_b32_dpp v47, v135 row_ror:8 row_mask:0xf bank_mask:0xc
	v_mov_b32_e32 v132, v32
	v_mov_b32_e32 v133, v33
	v_mov_b32_e32 v134, v34
	v_mov_b32_e32 v135, v35
	v_mov_b32_dpp v32, v36 row_ror:8 row_mask:0xf bank_mask:0x3
	v_mov_b32_dpp v33, v37 row_ror:8 row_mask:0xf bank_mask:0x3
	v_mov_b32_dpp v34, v38 row_ror:8 row_mask:0xf bank_mask:0x3
	v_mov_b32_dpp v35, v39 row_ror:8 row_mask:0xf bank_mask:0x3
	v_mov_b32_dpp v36, v132 row_ror:8 row_mask:0xf bank_mask:0xc
	v_mov_b32_dpp v37, v133 row_ror:8 row_mask:0xf bank_mask:0xc
	v_mov_b32_dpp v38, v134 row_ror:8 row_mask:0xf bank_mask:0xc
	v_mov_b32_dpp v39, v135 row_ror:8 row_mask:0xf bank_mask:0xc
	v_mov_b32_e32 v132, v24
	v_mov_b32_e32 v133, v25
	v_mov_b32_e32 v134, v26
	v_mov_b32_e32 v135, v27
	v_mov_b32_dpp v24, v28 row_ror:8 row_mask:0xf bank_mask:0x3
	v_mov_b32_dpp v25, v29 row_ror:8 row_mask:0xf bank_mask:0x3
	v_mov_b32_dpp v26, v30 row_ror:8 row_mask:0xf bank_mask:0x3
	v_mov_b32_dpp v27, v31 row_ror:8 row_mask:0xf bank_mask:0x3
	v_mov_b32_dpp v28, v132 row_ror:8 row_mask:0xf bank_mask:0xc
	v_mov_b32_dpp v29, v133 row_ror:8 row_mask:0xf bank_mask:0xc
	v_mov_b32_dpp v30, v134 row_ror:8 row_mask:0xf bank_mask:0xc
	v_mov_b32_dpp v31, v135 row_ror:8 row_mask:0xf bank_mask:0xc
	v_mov_b32_e32 v132, v16
	v_mov_b32_e32 v133, v17
	v_mov_b32_e32 v134, v18
	v_mov_b32_e32 v135, v19
	v_mov_b32_dpp v16, v20 row_ror:8 row_mask:0xf bank_mask:0x3
	v_mov_b32_dpp v17, v21 row_ror:8 row_mask:0xf bank_mask:0x3
	v_mov_b32_dpp v18, v22 row_ror:8 row_mask:0xf bank_mask:0x3
	v_mov_b32_dpp v19, v23 row_ror:8 row_mask:0xf bank_mask:0x3
	v_mov_b32_dpp v20, v132 row_ror:8 row_mask:0xf bank_mask:0xc
	v_mov_b32_dpp v21, v133 row_ror:8 row_mask:0xf bank_mask:0xc
	v_mov_b32_dpp v22, v134 row_ror:8 row_mask:0xf bank_mask:0xc
	v_mov_b32_dpp v23, v135 row_ror:8 row_mask:0xf bank_mask:0xc
	v_mov_b32_e32 v132, v8
	v_mov_b32_e32 v133, v9
	v_mov_b32_e32 v134, v10
	v_mov_b32_e32 v135, v11
	v_mov_b32_dpp v8, v12 row_ror:8 row_mask:0xf bank_mask:0x3
	v_mov_b32_dpp v9, v13 row_ror:8 row_mask:0xf bank_mask:0x3
	v_mov_b32_dpp v10, v14 row_ror:8 row_mask:0xf bank_mask:0x3
	v_mov_b32_dpp v11, v15 row_ror:8 row_mask:0xf bank_mask:0x3
	v_mov_b32_dpp v12, v132 row_ror:8 row_mask:0xf bank_mask:0xc
	v_mov_b32_dpp v13, v133 row_ror:8 row_mask:0xf bank_mask:0xc
	v_mov_b32_dpp v14, v134 row_ror:8 row_mask:0xf bank_mask:0xc
	v_mov_b32_dpp v15, v135 row_ror:8 row_mask:0xf bank_mask:0xc
	v_mov_b32_e32 v132, v0
	v_mov_b32_e32 v133, v1
	v_mov_b32_e32 v134, v2
	v_mov_b32_e32 v135, v3
	v_mov_b32_dpp v0, v4 row_ror:8 row_mask:0xf bank_mask:0x3
	v_mov_b32_dpp v1, v5 row_ror:8 row_mask:0xf bank_mask:0x3
	v_mov_b32_dpp v2, v6 row_ror:8 row_mask:0xf bank_mask:0x3
	v_mov_b32_dpp v3, v7 row_ror:8 row_mask:0xf bank_mask:0x3
	v_mov_b32_dpp v4, v132 row_ror:8 row_mask:0xf bank_mask:0xc
	v_mov_b32_dpp v5, v133 row_ror:8 row_mask:0xf bank_mask:0xc
	v_mov_b32_dpp v6, v134 row_ror:8 row_mask:0xf bank_mask:0xc
	v_mov_b32_dpp v7, v135 row_ror:8 row_mask:0xf bank_mask:0xc
	v_add_u32_e32 v206, 0x0, v224
	v_add_u32_e32 v207, 0x10000, v224
	v_add_u32_e32 v208, 0x20000, v224
	v_add_u32_e32 v209, 0x30000, v224
	global_load_dwordx4 v[112:115], v206, s[60:61]
	global_load_dwordx4 v[116:119], v206, s[60:61] offset:512
	global_load_dwordx4 v[120:123], v207, s[60:61]
	global_load_dwordx4 v[124:127], v207, s[60:61] offset:512
	global_load_dwordx4 v[148:151], v208, s[60:61]
	global_load_dwordx4 v[152:155], v208, s[60:61] offset:512
	global_load_dwordx4 v[156:159], v209, s[60:61]
	global_load_dwordx4 v[164:167], v209, s[60:61] offset:512
	v_add_u32_e32 v210, 0x40000, v224
	v_add_u32_e32 v211, 0x50000, v224
	v_add_u32_e32 v222, 0x60000, v224
	v_add_u32_e32 v223, 0x70000, v224
	global_load_dwordx4 v[168:171], v210, s[60:61]
	global_load_dwordx4 v[172:175], v210, s[60:61] offset:512
	global_load_dwordx4 v[176:179], v211, s[60:61]
	global_load_dwordx4 v[180:183], v211, s[60:61] offset:512
	global_load_dwordx4 v[184:187], v222, s[60:61]
	global_load_dwordx4 v[194:197], v222, s[60:61] offset:512
	global_load_dwordx4 v[198:201], v223, s[60:61]
	global_load_dwordx4 v[202:205], v223, s[60:61] offset:512
	s_waitcnt vmcnt(8)
; __device__ __forceinline__ unsigned cvt_pk_bf16(float lo, float hi) { typedef float f2_t __attribute__((ext_vector_type(2))); typedef __bf16 b2_t __attribute__((ext_vector_type(2))); const f2_t v = {lo, hi}; return __builtin_bit_cast(unsigned, __builtin_convertvector(v, b2_t)); }
;     __device__ __forceinline__ void operator()(const f32x4 (&acc)[2][2][4][2], const Unit& u, int wr, int wc, int fr, int fq) const {
;     ...
;             if (ch > 0) {
;                 const int pc = ch - 1, ai = pc >> 1;
; #pragma unroll
;                 for (int mm = 0; mm < 2; ++mm) { const int m = (pc & 1) * 2 + mm, row = row0 + ai * HALF + m * 16; const size_t off = (size_t)row * ldc + col0;
;                     float s = 0.f;
; #pragma unroll
;                     for (int bj = 0; bj < 2; ++bj)
; #pragma unroll
;                         for (int n = 0; n < 2; ++n) {
;                             const f32x4 o = b[pc & 1][mm][bj][n] + acc[ai][bj][m][n] * scale;
;                             *(f32x4*)(out + off + bj * HALF + n * 16) = o;
;                             if (NORM) { s += (o[0] * o[0] + o[1] * o[1]) + (o[2] * o[2] + o[3] * o[3]);
;                                 u32x2 w; w.x = cvt_pk_bf16(o[0], o[1]); w.y = cvt_pk_bf16(o[2], o[3]); *(u32x2*)(xb + off + bj * HALF + n * 16) = w; }
;                         }
;                     if (NORM) { s += __shfl_xor(s, 16); s += __shfl_xor(s, 32); ssq[(size_t)row * 32 + u.pn * 4 + wc] = s; }
;                 }
	v_pk_fma_f32 v[160:161], v[160:161], 0.5, v[112:113] op_sel_hi:[1,0,1]
	v_pk_fma_f32 v[162:163], v[162:163], 0.5, v[114:115] op_sel_hi:[1,0,1]
	v_pk_fma_f32 v[136:137], v[136:137], 0.5, v[116:117] op_sel_hi:[1,0,1]
	v_pk_fma_f32 v[138:139], v[138:139], 0.5, v[118:119] op_sel_hi:[1,0,1]
	v_pk_fma_f32 v[144:145], v[144:145], 0.5, v[120:121] op_sel_hi:[1,0,1]
	v_pk_fma_f32 v[146:147], v[146:147], 0.5, v[122:123] op_sel_hi:[1,0,1]
	v_pk_fma_f32 v[128:129], v[128:129], 0.5, v[124:125] op_sel_hi:[1,0,1]
	v_pk_fma_f32 v[130:131], v[130:131], 0.5, v[126:127] op_sel_hi:[1,0,1]
	v_pk_fma_f32 v[108:109], v[108:109], 0.5, v[148:149] op_sel_hi:[1,0,1]
	v_pk_fma_f32 v[110:111], v[110:111], 0.5, v[150:151] op_sel_hi:[1,0,1]
	v_pk_fma_f32 v[100:101], v[100:101], 0.5, v[152:153] op_sel_hi:[1,0,1]
	v_pk_fma_f32 v[102:103], v[102:103], 0.5, v[154:155] op_sel_hi:[1,0,1]
	v_pk_fma_f32 v[104:105], v[104:105], 0.5, v[156:157] op_sel_hi:[1,0,1]
	v_pk_fma_f32 v[106:107], v[106:107], 0.5, v[158:159] op_sel_hi:[1,0,1]
	v_pk_fma_f32 v[96:97], v[96:97], 0.5, v[164:165] op_sel_hi:[1,0,1]
	v_pk_fma_f32 v[98:99], v[98:99], 0.5, v[166:167] op_sel_hi:[1,0,1]
	global_store_dwordx4 v206, v[160:163], s[88:89]
	global_store_dwordx4 v206, v[136:139], s[88:89] offset:512
	global_store_dwordx4 v207, v[144:147], s[88:89]
	global_store_dwordx4 v207, v[128:131], s[88:89] offset:512
	global_store_dwordx4 v208, v[108:111], s[88:89]
	global_store_dwordx4 v208, v[100:103], s[88:89] offset:512
	global_store_dwordx4 v209, v[104:107], s[88:89]
	global_store_dwordx4 v209, v[96:99], s[88:89] offset:512
	v_mul_f32_e32 v235, v160, v160
	v_fmac_f32_e32 v235, v161, v161
	v_fmac_f32_e32 v235, v162, v162
	v_fmac_f32_e32 v235, v163, v163
	v_fmac_f32_e32 v235, v136, v136
	v_fmac_f32_e32 v235, v137, v137
	v_fmac_f32_e32 v235, v138, v138
	v_fmac_f32_e32 v235, v139, v139
	v_mul_f32_e32 v236, v144, v144
	v_fmac_f32_e32 v236, v145, v145
	v_fmac_f32_e32 v236, v146, v146
	v_fmac_f32_e32 v236, v147, v147
	v_fmac_f32_e32 v236, v128, v128
	v_fmac_f32_e32 v236, v129, v129
	v_fmac_f32_e32 v236, v130, v130
	v_fmac_f32_e32 v236, v131, v131
	v_mul_f32_e32 v237, v108, v108
	v_fmac_f32_e32 v237, v109, v109
	v_fmac_f32_e32 v237, v110, v110
	v_fmac_f32_e32 v237, v111, v111
	v_fmac_f32_e32 v237, v100, v100
	v_fmac_f32_e32 v237, v101, v101
	v_fmac_f32_e32 v237, v102, v102
	v_fmac_f32_e32 v237, v103, v103
	v_mul_f32_e32 v238, v104, v104
	v_fmac_f32_e32 v238, v105, v105
	v_fmac_f32_e32 v238, v106, v106
	v_fmac_f32_e32 v238, v107, v107
	v_fmac_f32_e32 v238, v96, v96
	v_fmac_f32_e32 v238, v97, v97
	v_fmac_f32_e32 v238, v98, v98
	v_fmac_f32_e32 v238, v99, v99
	v_cvt_pk_bf16_f32 v112, v160, v161
	v_cvt_pk_bf16_f32 v113, v162, v163
	v_cvt_pk_bf16_f32 v116, v136, v137
	v_cvt_pk_bf16_f32 v117, v138, v139
	v_cvt_pk_bf16_f32 v120, v144, v145
	v_cvt_pk_bf16_f32 v121, v146, v147
	v_cvt_pk_bf16_f32 v124, v128, v129
	v_cvt_pk_bf16_f32 v125, v130, v131
	v_cvt_pk_bf16_f32 v148, v108, v109
	v_cvt_pk_bf16_f32 v149, v110, v111
	v_cvt_pk_bf16_f32 v152, v100, v101
	v_cvt_pk_bf16_f32 v153, v102, v103
	v_cvt_pk_bf16_f32 v156, v104, v105
	v_cvt_pk_bf16_f32 v157, v106, v107
	v_cvt_pk_bf16_f32 v164, v96, v97
	v_cvt_pk_bf16_f32 v165, v98, v99
	v_add_u32_e32 v239, 0x0, v234
	v_add_u32_e32 v240, 0x8000, v234
	v_add_u32_e32 v241, 0x10000, v234
	v_add_u32_e32 v242, 0x18000, v234
	global_store_dwordx2 v239, v[112:113], s[36:37]
	global_store_dwordx2 v239, v[116:117], s[36:37] offset:256
	global_store_dwordx2 v240, v[120:121], s[36:37]
	global_store_dwordx2 v240, v[124:125], s[36:37] offset:256
	global_store_dwordx2 v241, v[148:149], s[36:37]
	global_store_dwordx2 v241, v[152:153], s[36:37] offset:256
	global_store_dwordx2 v242, v[156:157], s[36:37]
	global_store_dwordx2 v242, v[164:165], s[36:37] offset:256
	ds_bpermute_b32 v243, v230, v235
	ds_bpermute_b32 v244, v230, v236
	ds_bpermute_b32 v245, v230, v237
	ds_bpermute_b32 v246, v230, v238
	s_waitcnt lgkmcnt(0)
	v_add_f32_e32 v235, v235, v243
	v_add_f32_e32 v236, v236, v244
	v_add_f32_e32 v237, v237, v245
	v_add_f32_e32 v238, v238, v246
	ds_bpermute_b32 v243, v231, v235
	ds_bpermute_b32 v244, v231, v236
	ds_bpermute_b32 v245, v231, v237
	ds_bpermute_b32 v246, v231, v238
	s_waitcnt lgkmcnt(0)
	v_add_f32_e32 v235, v235, v243
	v_add_f32_e32 v236, v236, v244
	v_add_f32_e32 v237, v237, v245
	v_add_f32_e32 v238, v238, v246
	s_nop 1
	v_add_f32_dpp v243, v235, v235 row_ror:8 row_mask:0xf bank_mask:0xf
	v_add_f32_dpp v244, v236, v236 row_ror:8 row_mask:0xf bank_mask:0xf
	v_add_f32_dpp v245, v237, v237 row_ror:8 row_mask:0xf bank_mask:0xf
	v_add_f32_dpp v246, v238, v238 row_ror:8 row_mask:0xf bank_mask:0xf
	v_cndmask_b32_e64 v247, v243, v244, s[62:63]
	v_add_u32_e32 v249, 0x0, v232
	v_cndmask_b32_e64 v248, v245, v246, s[62:63]
	v_add_u32_e32 v250, 0x800, v232
	global_store_dword v249, v247, s[48:49]
	global_store_dword v250, v248, s[48:49]
	v_add_u32_e32 v206, 0x100000, v224
	v_add_u32_e32 v207, 0x110000, v224
	v_add_u32_e32 v208, 0x120000, v224
	v_add_u32_e32 v209, 0x130000, v224
	global_load_dwordx4 v[112:115], v206, s[60:61]
	global_load_dwordx4 v[116:119], v206, s[60:61] offset:512
	global_load_dwordx4 v[120:123], v207, s[60:61]
	global_load_dwordx4 v[124:127], v207, s[60:61] offset:512
	global_load_dwordx4 v[148:151], v208, s[60:61]
	global_load_dwordx4 v[152:155], v208, s[60:61] offset:512
	global_load_dwordx4 v[156:159], v209, s[60:61]
	global_load_dwordx4 v[164:167], v209, s[60:61] offset:512
	s_waitcnt vmcnt(26)
; __device__ __forceinline__ unsigned cvt_pk_bf16(float lo, float hi) { typedef float f2_t __attribute__((ext_vector_type(2))); typedef __bf16 b2_t __attribute__((ext_vector_type(2))); const f2_t v = {lo, hi}; return __builtin_bit_cast(unsigned, __builtin_convertvector(v, b2_t)); }
;     __device__ __forceinline__ void operator()(const f32x4 (&acc)[2][2][4][2], const Unit& u, int wr, int wc, int fr, int fq) const {
;     ...
;             if (ch > 0) {
;                 const int pc = ch - 1, ai = pc >> 1;
; #pragma unroll
;                 for (int mm = 0; mm < 2; ++mm) { const int m = (pc & 1) * 2 + mm, row = row0 + ai * HALF + m * 16; const size_t off = (size_t)row * ldc + col0;
;                     float s = 0.f;
; #pragma unroll
;                     for (int bj = 0; bj < 2; ++bj)
; #pragma unroll
;                         for (int n = 0; n < 2; ++n) {
;                             const f32x4 o = b[pc & 1][mm][bj][n] + acc[ai][bj][m][n] * scale;
;                             *(f32x4*)(out + off + bj * HALF + n * 16) = o;
;                             if (NORM) { s += (o[0] * o[0] + o[1] * o[1]) + (o[2] * o[2] + o[3] * o[3]);
;                                 u32x2 w; w.x = cvt_pk_bf16(o[0], o[1]); w.y = cvt_pk_bf16(o[2], o[3]); *(u32x2*)(xb + off + bj * HALF + n * 16) = w; }
;                         }
;                     if (NORM) { s += __shfl_xor(s, 16); s += __shfl_xor(s, 32); ssq[(size_t)row * 32 + u.pn * 4 + wc] = s; }
;                 }
	v_pk_fma_f32 v[92:93], v[92:93], 0.5, v[168:169] op_sel_hi:[1,0,1]
	v_pk_fma_f32 v[94:95], v[94:95], 0.5, v[170:171] op_sel_hi:[1,0,1]
	v_pk_fma_f32 v[84:85], v[84:85], 0.5, v[172:173] op_sel_hi:[1,0,1]
	v_pk_fma_f32 v[86:87], v[86:87], 0.5, v[174:175] op_sel_hi:[1,0,1]
	v_pk_fma_f32 v[88:89], v[88:89], 0.5, v[176:177] op_sel_hi:[1,0,1]
	v_pk_fma_f32 v[90:91], v[90:91], 0.5, v[178:179] op_sel_hi:[1,0,1]
	v_pk_fma_f32 v[80:81], v[80:81], 0.5, v[180:181] op_sel_hi:[1,0,1]
	v_pk_fma_f32 v[82:83], v[82:83], 0.5, v[182:183] op_sel_hi:[1,0,1]
	v_pk_fma_f32 v[76:77], v[76:77], 0.5, v[184:185] op_sel_hi:[1,0,1]
	v_pk_fma_f32 v[78:79], v[78:79], 0.5, v[186:187] op_sel_hi:[1,0,1]
	v_pk_fma_f32 v[68:69], v[68:69], 0.5, v[194:195] op_sel_hi:[1,0,1]
	v_pk_fma_f32 v[70:71], v[70:71], 0.5, v[196:197] op_sel_hi:[1,0,1]
	v_pk_fma_f32 v[72:73], v[72:73], 0.5, v[198:199] op_sel_hi:[1,0,1]
	v_pk_fma_f32 v[74:75], v[74:75], 0.5, v[200:201] op_sel_hi:[1,0,1]
	v_pk_fma_f32 v[64:65], v[64:65], 0.5, v[202:203] op_sel_hi:[1,0,1]
	v_pk_fma_f32 v[66:67], v[66:67], 0.5, v[204:205] op_sel_hi:[1,0,1]
	global_store_dwordx4 v210, v[92:95], s[88:89]
	global_store_dwordx4 v210, v[84:87], s[88:89] offset:512
	global_store_dwordx4 v211, v[88:91], s[88:89]
	global_store_dwordx4 v211, v[80:83], s[88:89] offset:512
	global_store_dwordx4 v222, v[76:79], s[88:89]
	global_store_dwordx4 v222, v[68:71], s[88:89] offset:512
	global_store_dwordx4 v223, v[72:75], s[88:89]
	global_store_dwordx4 v223, v[64:67], s[88:89] offset:512
	v_mul_f32_e32 v235, v92, v92
	v_fmac_f32_e32 v235, v93, v93
	v_fmac_f32_e32 v235, v94, v94
	v_fmac_f32_e32 v235, v95, v95
	v_fmac_f32_e32 v235, v84, v84
	v_fmac_f32_e32 v235, v85, v85
	v_fmac_f32_e32 v235, v86, v86
	v_fmac_f32_e32 v235, v87, v87
	v_mul_f32_e32 v236, v88, v88
	v_fmac_f32_e32 v236, v89, v89
	v_fmac_f32_e32 v236, v90, v90
	v_fmac_f32_e32 v236, v91, v91
	v_fmac_f32_e32 v236, v80, v80
	v_fmac_f32_e32 v236, v81, v81
	v_fmac_f32_e32 v236, v82, v82
	v_fmac_f32_e32 v236, v83, v83
	v_mul_f32_e32 v237, v76, v76
	v_fmac_f32_e32 v237, v77, v77
	v_fmac_f32_e32 v237, v78, v78
	v_fmac_f32_e32 v237, v79, v79
	v_fmac_f32_e32 v237, v68, v68
	v_fmac_f32_e32 v237, v69, v69
	v_fmac_f32_e32 v237, v70, v70
	v_fmac_f32_e32 v237, v71, v71
	v_mul_f32_e32 v238, v72, v72
	v_fmac_f32_e32 v238, v73, v73
	v_fmac_f32_e32 v238, v74, v74
	v_fmac_f32_e32 v238, v75, v75
	v_fmac_f32_e32 v238, v64, v64
	v_fmac_f32_e32 v238, v65, v65
	v_fmac_f32_e32 v238, v66, v66
	v_fmac_f32_e32 v238, v67, v67
	v_cvt_pk_bf16_f32 v168, v92, v93
	v_cvt_pk_bf16_f32 v169, v94, v95
	v_cvt_pk_bf16_f32 v172, v84, v85
	v_cvt_pk_bf16_f32 v173, v86, v87
	v_cvt_pk_bf16_f32 v176, v88, v89
	v_cvt_pk_bf16_f32 v177, v90, v91
	v_cvt_pk_bf16_f32 v180, v80, v81
	v_cvt_pk_bf16_f32 v181, v82, v83
	v_cvt_pk_bf16_f32 v184, v76, v77
	v_cvt_pk_bf16_f32 v185, v78, v79
	v_cvt_pk_bf16_f32 v194, v68, v69
	v_cvt_pk_bf16_f32 v195, v70, v71
	v_cvt_pk_bf16_f32 v198, v72, v73
	v_cvt_pk_bf16_f32 v199, v74, v75
	v_cvt_pk_bf16_f32 v202, v64, v65
	v_cvt_pk_bf16_f32 v203, v66, v67
	v_add_u32_e32 v239, 0x20000, v234
	v_add_u32_e32 v240, 0x28000, v234
	v_add_u32_e32 v241, 0x30000, v234
	v_add_u32_e32 v242, 0x38000, v234
	global_store_dwordx2 v239, v[168:169], s[36:37]
	global_store_dwordx2 v239, v[172:173], s[36:37] offset:256
	global_store_dwordx2 v240, v[176:177], s[36:37]
	global_store_dwordx2 v240, v[180:181], s[36:37] offset:256
	global_store_dwordx2 v241, v[184:185], s[36:37]
	global_store_dwordx2 v241, v[194:195], s[36:37] offset:256
	global_store_dwordx2 v242, v[198:199], s[36:37]
	global_store_dwordx2 v242, v[202:203], s[36:37] offset:256
	ds_bpermute_b32 v243, v230, v235
	ds_bpermute_b32 v244, v230, v236
	ds_bpermute_b32 v245, v230, v237
	ds_bpermute_b32 v246, v230, v238
	s_waitcnt lgkmcnt(0)
	v_add_f32_e32 v235, v235, v243
	v_add_f32_e32 v236, v236, v244
	v_add_f32_e32 v237, v237, v245
	v_add_f32_e32 v238, v238, v246
	ds_bpermute_b32 v243, v231, v235
	ds_bpermute_b32 v244, v231, v236
	ds_bpermute_b32 v245, v231, v237
	ds_bpermute_b32 v246, v231, v238
	s_waitcnt lgkmcnt(0)
	v_add_f32_e32 v235, v235, v243
	v_add_f32_e32 v236, v236, v244
	v_add_f32_e32 v237, v237, v245
	v_add_f32_e32 v238, v238, v246
	s_nop 1
	v_add_f32_dpp v243, v235, v235 row_ror:8 row_mask:0xf bank_mask:0xf
	v_add_f32_dpp v244, v236, v236 row_ror:8 row_mask:0xf bank_mask:0xf
	v_add_f32_dpp v245, v237, v237 row_ror:8 row_mask:0xf bank_mask:0xf
	v_add_f32_dpp v246, v238, v238 row_ror:8 row_mask:0xf bank_mask:0xf
	v_cndmask_b32_e64 v247, v243, v244, s[62:63]
	v_add_u32_e32 v249, 0x1000, v232
	v_cndmask_b32_e64 v248, v245, v246, s[62:63]
	v_add_u32_e32 v250, 0x1800, v232
	global_store_dword v249, v247, s[48:49]
	global_store_dword v250, v248, s[48:49]
	v_add_u32_e32 v210, 0x140000, v224
	v_add_u32_e32 v211, 0x150000, v224
	v_add_u32_e32 v222, 0x160000, v224
	v_add_u32_e32 v223, 0x170000, v224
	global_load_dwordx4 v[168:171], v210, s[60:61]
	global_load_dwordx4 v[172:175], v210, s[60:61] offset:512
	global_load_dwordx4 v[176:179], v211, s[60:61]
	global_load_dwordx4 v[180:183], v211, s[60:61] offset:512
	global_load_dwordx4 v[184:187], v222, s[60:61]
	global_load_dwordx4 v[194:197], v222, s[60:61] offset:512
	global_load_dwordx4 v[198:201], v223, s[60:61]
	global_load_dwordx4 v[202:205], v223, s[60:61] offset:512
	s_waitcnt vmcnt(26)
; __device__ __forceinline__ unsigned cvt_pk_bf16(float lo, float hi) { typedef float f2_t __attribute__((ext_vector_type(2))); typedef __bf16 b2_t __attribute__((ext_vector_type(2))); const f2_t v = {lo, hi}; return __builtin_bit_cast(unsigned, __builtin_convertvector(v, b2_t)); }
;     __device__ __forceinline__ void operator()(const f32x4 (&acc)[2][2][4][2], const Unit& u, int wr, int wc, int fr, int fq) const {
;     ...
;             if (ch > 0) {
;                 const int pc = ch - 1, ai = pc >> 1;
; #pragma unroll
;                 for (int mm = 0; mm < 2; ++mm) { const int m = (pc & 1) * 2 + mm, row = row0 + ai * HALF + m * 16; const size_t off = (size_t)row * ldc + col0;
;                     float s = 0.f;
; #pragma unroll
;                     for (int bj = 0; bj < 2; ++bj)
; #pragma unroll
;                         for (int n = 0; n < 2; ++n) {
;                             const f32x4 o = b[pc & 1][mm][bj][n] + acc[ai][bj][m][n] * scale;
;                             *(f32x4*)(out + off + bj * HALF + n * 16) = o;
;                             if (NORM) { s += (o[0] * o[0] + o[1] * o[1]) + (o[2] * o[2] + o[3] * o[3]);
;                                 u32x2 w; w.x = cvt_pk_bf16(o[0], o[1]); w.y = cvt_pk_bf16(o[2], o[3]); *(u32x2*)(xb + off + bj * HALF + n * 16) = w; }
;                         }
;                     if (NORM) { s += __shfl_xor(s, 16); s += __shfl_xor(s, 32); ssq[(size_t)row * 32 + u.pn * 4 + wc] = s; }
;                 }
	v_pk_fma_f32 v[60:61], v[60:61], 0.5, v[112:113] op_sel_hi:[1,0,1]
	v_pk_fma_f32 v[62:63], v[62:63], 0.5, v[114:115] op_sel_hi:[1,0,1]
	v_pk_fma_f32 v[52:53], v[52:53], 0.5, v[116:117] op_sel_hi:[1,0,1]
	v_pk_fma_f32 v[54:55], v[54:55], 0.5, v[118:119] op_sel_hi:[1,0,1]
	v_pk_fma_f32 v[56:57], v[56:57], 0.5, v[120:121] op_sel_hi:[1,0,1]
	v_pk_fma_f32 v[58:59], v[58:59], 0.5, v[122:123] op_sel_hi:[1,0,1]
	v_pk_fma_f32 v[48:49], v[48:49], 0.5, v[124:125] op_sel_hi:[1,0,1]
	v_pk_fma_f32 v[50:51], v[50:51], 0.5, v[126:127] op_sel_hi:[1,0,1]
	v_pk_fma_f32 v[44:45], v[44:45], 0.5, v[148:149] op_sel_hi:[1,0,1]
	v_pk_fma_f32 v[46:47], v[46:47], 0.5, v[150:151] op_sel_hi:[1,0,1]
	v_pk_fma_f32 v[36:37], v[36:37], 0.5, v[152:153] op_sel_hi:[1,0,1]
	v_pk_fma_f32 v[38:39], v[38:39], 0.5, v[154:155] op_sel_hi:[1,0,1]
	v_pk_fma_f32 v[40:41], v[40:41], 0.5, v[156:157] op_sel_hi:[1,0,1]
	v_pk_fma_f32 v[42:43], v[42:43], 0.5, v[158:159] op_sel_hi:[1,0,1]
	v_pk_fma_f32 v[32:33], v[32:33], 0.5, v[164:165] op_sel_hi:[1,0,1]
	v_pk_fma_f32 v[34:35], v[34:35], 0.5, v[166:167] op_sel_hi:[1,0,1]
	global_store_dwordx4 v206, v[60:63], s[88:89]
	global_store_dwordx4 v206, v[52:55], s[88:89] offset:512
	global_store_dwordx4 v207, v[56:59], s[88:89]
	global_store_dwordx4 v207, v[48:51], s[88:89] offset:512
	global_store_dwordx4 v208, v[44:47], s[88:89]
	global_store_dwordx4 v208, v[36:39], s[88:89] offset:512
	global_store_dwordx4 v209, v[40:43], s[88:89]
	global_store_dwordx4 v209, v[32:35], s[88:89] offset:512
	v_mul_f32_e32 v235, v60, v60
	v_fmac_f32_e32 v235, v61, v61
	v_fmac_f32_e32 v235, v62, v62
	v_fmac_f32_e32 v235, v63, v63
	v_fmac_f32_e32 v235, v52, v52
	v_fmac_f32_e32 v235, v53, v53
	v_fmac_f32_e32 v235, v54, v54
	v_fmac_f32_e32 v235, v55, v55
	v_mul_f32_e32 v236, v56, v56
	v_fmac_f32_e32 v236, v57, v57
	v_fmac_f32_e32 v236, v58, v58
	v_fmac_f32_e32 v236, v59, v59
	v_fmac_f32_e32 v236, v48, v48
	v_fmac_f32_e32 v236, v49, v49
	v_fmac_f32_e32 v236, v50, v50
	v_fmac_f32_e32 v236, v51, v51
	v_mul_f32_e32 v237, v44, v44
	v_fmac_f32_e32 v237, v45, v45
	v_fmac_f32_e32 v237, v46, v46
	v_fmac_f32_e32 v237, v47, v47
	v_fmac_f32_e32 v237, v36, v36
	v_fmac_f32_e32 v237, v37, v37
	v_fmac_f32_e32 v237, v38, v38
	v_fmac_f32_e32 v237, v39, v39
	v_mul_f32_e32 v238, v40, v40
	v_fmac_f32_e32 v238, v41, v41
	v_fmac_f32_e32 v238, v42, v42
	v_fmac_f32_e32 v238, v43, v43
	v_fmac_f32_e32 v238, v32, v32
	v_fmac_f32_e32 v238, v33, v33
	v_fmac_f32_e32 v238, v34, v34
	v_fmac_f32_e32 v238, v35, v35
	v_cvt_pk_bf16_f32 v112, v60, v61
	v_cvt_pk_bf16_f32 v113, v62, v63
	v_cvt_pk_bf16_f32 v116, v52, v53
	v_cvt_pk_bf16_f32 v117, v54, v55
	v_cvt_pk_bf16_f32 v120, v56, v57
	v_cvt_pk_bf16_f32 v121, v58, v59
	v_cvt_pk_bf16_f32 v124, v48, v49
	v_cvt_pk_bf16_f32 v125, v50, v51
	v_cvt_pk_bf16_f32 v148, v44, v45
	v_cvt_pk_bf16_f32 v149, v46, v47
	v_cvt_pk_bf16_f32 v152, v36, v37
	v_cvt_pk_bf16_f32 v153, v38, v39
	v_cvt_pk_bf16_f32 v156, v40, v41
	v_cvt_pk_bf16_f32 v157, v42, v43
	v_cvt_pk_bf16_f32 v164, v32, v33
	v_cvt_pk_bf16_f32 v165, v34, v35
	v_add_u32_e32 v239, 0x80000, v234
	v_add_u32_e32 v240, 0x88000, v234
	v_add_u32_e32 v241, 0x90000, v234
	v_add_u32_e32 v242, 0x98000, v234
	global_store_dwordx2 v239, v[112:113], s[36:37]
	global_store_dwordx2 v239, v[116:117], s[36:37] offset:256
	global_store_dwordx2 v240, v[120:121], s[36:37]
	global_store_dwordx2 v240, v[124:125], s[36:37] offset:256
	global_store_dwordx2 v241, v[148:149], s[36:37]
	global_store_dwordx2 v241, v[152:153], s[36:37] offset:256
	global_store_dwordx2 v242, v[156:157], s[36:37]
	global_store_dwordx2 v242, v[164:165], s[36:37] offset:256
	ds_bpermute_b32 v243, v230, v235
	ds_bpermute_b32 v244, v230, v236
	ds_bpermute_b32 v245, v230, v237
	ds_bpermute_b32 v246, v230, v238
	s_waitcnt lgkmcnt(0)
	v_add_f32_e32 v235, v235, v243
	v_add_f32_e32 v236, v236, v244
	v_add_f32_e32 v237, v237, v245
	v_add_f32_e32 v238, v238, v246
	ds_bpermute_b32 v243, v231, v235
	ds_bpermute_b32 v244, v231, v236
	ds_bpermute_b32 v245, v231, v237
	ds_bpermute_b32 v246, v231, v238
	s_waitcnt lgkmcnt(0)
	v_add_f32_e32 v235, v235, v243
	v_add_f32_e32 v236, v236, v244
	v_add_f32_e32 v237, v237, v245
	v_add_f32_e32 v238, v238, v246
	s_nop 1
	v_add_f32_dpp v243, v235, v235 row_ror:8 row_mask:0xf bank_mask:0xf
	v_add_f32_dpp v244, v236, v236 row_ror:8 row_mask:0xf bank_mask:0xf
	v_add_f32_dpp v245, v237, v237 row_ror:8 row_mask:0xf bank_mask:0xf
	v_add_f32_dpp v246, v238, v238 row_ror:8 row_mask:0xf bank_mask:0xf
	v_cndmask_b32_e64 v247, v243, v244, s[62:63]
	v_add_u32_e32 v249, 0x4000, v232
	v_cndmask_b32_e64 v248, v245, v246, s[62:63]
	v_add_u32_e32 v250, 0x4800, v232
	global_store_dword v249, v247, s[48:49]
	global_store_dword v250, v248, s[48:49]
	s_waitcnt vmcnt(18)
; __device__ __forceinline__ unsigned cvt_pk_bf16(float lo, float hi) { typedef float f2_t __attribute__((ext_vector_type(2))); typedef __bf16 b2_t __attribute__((ext_vector_type(2))); const f2_t v = {lo, hi}; return __builtin_bit_cast(unsigned, __builtin_convertvector(v, b2_t)); }
;     __device__ __forceinline__ void operator()(const f32x4 (&acc)[2][2][4][2], const Unit& u, int wr, int wc, int fr, int fq) const {
;     ...
;             if (ch > 0) {
;                 const int pc = ch - 1, ai = pc >> 1;
; #pragma unroll
;                 for (int mm = 0; mm < 2; ++mm) { const int m = (pc & 1) * 2 + mm, row = row0 + ai * HALF + m * 16; const size_t off = (size_t)row * ldc + col0;
;                     float s = 0.f;
; #pragma unroll
;                     for (int bj = 0; bj < 2; ++bj)
; #pragma unroll
;                         for (int n = 0; n < 2; ++n) {
;                             const f32x4 o = b[pc & 1][mm][bj][n] + acc[ai][bj][m][n] * scale;
;                             *(f32x4*)(out + off + bj * HALF + n * 16) = o;
;                             if (NORM) { s += (o[0] * o[0] + o[1] * o[1]) + (o[2] * o[2] + o[3] * o[3]);
;                                 u32x2 w; w.x = cvt_pk_bf16(o[0], o[1]); w.y = cvt_pk_bf16(o[2], o[3]); *(u32x2*)(xb + off + bj * HALF + n * 16) = w; }
;                         }
;                     if (NORM) { s += __shfl_xor(s, 16); s += __shfl_xor(s, 32); ssq[(size_t)row * 32 + u.pn * 4 + wc] = s; }
;                 }
;             }
;             asm volatile("" ::: "memory");
;         }
;     }
	v_pk_fma_f32 v[28:29], v[28:29], 0.5, v[168:169] op_sel_hi:[1,0,1]
	v_pk_fma_f32 v[30:31], v[30:31], 0.5, v[170:171] op_sel_hi:[1,0,1]
	v_pk_fma_f32 v[20:21], v[20:21], 0.5, v[172:173] op_sel_hi:[1,0,1]
	v_pk_fma_f32 v[22:23], v[22:23], 0.5, v[174:175] op_sel_hi:[1,0,1]
	v_pk_fma_f32 v[24:25], v[24:25], 0.5, v[176:177] op_sel_hi:[1,0,1]
	v_pk_fma_f32 v[26:27], v[26:27], 0.5, v[178:179] op_sel_hi:[1,0,1]
	v_pk_fma_f32 v[16:17], v[16:17], 0.5, v[180:181] op_sel_hi:[1,0,1]
	v_pk_fma_f32 v[18:19], v[18:19], 0.5, v[182:183] op_sel_hi:[1,0,1]
	v_pk_fma_f32 v[12:13], v[12:13], 0.5, v[184:185] op_sel_hi:[1,0,1]
	v_pk_fma_f32 v[14:15], v[14:15], 0.5, v[186:187] op_sel_hi:[1,0,1]
	v_pk_fma_f32 v[4:5], v[4:5], 0.5, v[194:195] op_sel_hi:[1,0,1]
	v_pk_fma_f32 v[6:7], v[6:7], 0.5, v[196:197] op_sel_hi:[1,0,1]
	v_pk_fma_f32 v[8:9], v[8:9], 0.5, v[198:199] op_sel_hi:[1,0,1]
	v_pk_fma_f32 v[10:11], v[10:11], 0.5, v[200:201] op_sel_hi:[1,0,1]
	v_pk_fma_f32 v[0:1], v[0:1], 0.5, v[202:203] op_sel_hi:[1,0,1]
	v_pk_fma_f32 v[2:3], v[2:3], 0.5, v[204:205] op_sel_hi:[1,0,1]
	global_store_dwordx4 v210, v[28:31], s[88:89]
	global_store_dwordx4 v210, v[20:23], s[88:89] offset:512
	global_store_dwordx4 v211, v[24:27], s[88:89]
	global_store_dwordx4 v211, v[16:19], s[88:89] offset:512
	global_store_dwordx4 v222, v[12:15], s[88:89]
	global_store_dwordx4 v222, v[4:7], s[88:89] offset:512
	global_store_dwordx4 v223, v[8:11], s[88:89]
	global_store_dwordx4 v223, v[0:3], s[88:89] offset:512
	v_mul_f32_e32 v235, v28, v28
	v_fmac_f32_e32 v235, v29, v29
	v_fmac_f32_e32 v235, v30, v30
	v_fmac_f32_e32 v235, v31, v31
	v_fmac_f32_e32 v235, v20, v20
	v_fmac_f32_e32 v235, v21, v21
	v_fmac_f32_e32 v235, v22, v22
	v_fmac_f32_e32 v235, v23, v23
	v_mul_f32_e32 v236, v24, v24
	v_fmac_f32_e32 v236, v25, v25
	v_fmac_f32_e32 v236, v26, v26
	v_fmac_f32_e32 v236, v27, v27
	v_fmac_f32_e32 v236, v16, v16
	v_fmac_f32_e32 v236, v17, v17
	v_fmac_f32_e32 v236, v18, v18
	v_fmac_f32_e32 v236, v19, v19
	v_mul_f32_e32 v237, v12, v12
	v_fmac_f32_e32 v237, v13, v13
	v_fmac_f32_e32 v237, v14, v14
	v_fmac_f32_e32 v237, v15, v15
	v_fmac_f32_e32 v237, v4, v4
	v_fmac_f32_e32 v237, v5, v5
	v_fmac_f32_e32 v237, v6, v6
	v_fmac_f32_e32 v237, v7, v7
	v_mul_f32_e32 v238, v8, v8
	v_fmac_f32_e32 v238, v9, v9
	v_fmac_f32_e32 v238, v10, v10
	v_fmac_f32_e32 v238, v11, v11
	v_fmac_f32_e32 v238, v0, v0
	v_fmac_f32_e32 v238, v1, v1
	v_fmac_f32_e32 v238, v2, v2
	v_fmac_f32_e32 v238, v3, v3
	v_cvt_pk_bf16_f32 v168, v28, v29
	v_cvt_pk_bf16_f32 v169, v30, v31
	v_cvt_pk_bf16_f32 v172, v20, v21
	v_cvt_pk_bf16_f32 v173, v22, v23
	v_cvt_pk_bf16_f32 v176, v24, v25
	v_cvt_pk_bf16_f32 v177, v26, v27
	v_cvt_pk_bf16_f32 v180, v16, v17
	v_cvt_pk_bf16_f32 v181, v18, v19
	v_cvt_pk_bf16_f32 v184, v12, v13
	v_cvt_pk_bf16_f32 v185, v14, v15
	v_cvt_pk_bf16_f32 v194, v4, v5
	v_cvt_pk_bf16_f32 v195, v6, v7
	v_cvt_pk_bf16_f32 v198, v8, v9
	v_cvt_pk_bf16_f32 v199, v10, v11
	v_cvt_pk_bf16_f32 v202, v0, v1
	v_cvt_pk_bf16_f32 v203, v2, v3
	v_add_u32_e32 v239, 0xa0000, v234
	v_add_u32_e32 v240, 0xa8000, v234
	v_add_u32_e32 v241, 0xb0000, v234
	v_add_u32_e32 v242, 0xb8000, v234
	global_store_dwordx2 v239, v[168:169], s[36:37]
	global_store_dwordx2 v239, v[172:173], s[36:37] offset:256
	global_store_dwordx2 v240, v[176:177], s[36:37]
	global_store_dwordx2 v240, v[180:181], s[36:37] offset:256
	global_store_dwordx2 v241, v[184:185], s[36:37]
	global_store_dwordx2 v241, v[194:195], s[36:37] offset:256
	global_store_dwordx2 v242, v[198:199], s[36:37]
	global_store_dwordx2 v242, v[202:203], s[36:37] offset:256
	ds_bpermute_b32 v243, v230, v235
	ds_bpermute_b32 v244, v230, v236
	ds_bpermute_b32 v245, v230, v237
	ds_bpermute_b32 v246, v230, v238
	s_waitcnt lgkmcnt(0)
	v_add_f32_e32 v235, v235, v243
	v_add_f32_e32 v236, v236, v244
	v_add_f32_e32 v237, v237, v245
	v_add_f32_e32 v238, v238, v246
	ds_bpermute_b32 v243, v231, v235
	ds_bpermute_b32 v244, v231, v236
	ds_bpermute_b32 v245, v231, v237
	ds_bpermute_b32 v246, v231, v238
	s_waitcnt lgkmcnt(0)
	v_add_f32_e32 v235, v235, v243
	v_add_f32_e32 v236, v236, v244
	v_add_f32_e32 v237, v237, v245
	v_add_f32_e32 v238, v238, v246
	s_nop 1
	v_add_f32_dpp v243, v235, v235 row_ror:8 row_mask:0xf bank_mask:0xf
	v_add_f32_dpp v244, v236, v236 row_ror:8 row_mask:0xf bank_mask:0xf
	v_add_f32_dpp v245, v237, v237 row_ror:8 row_mask:0xf bank_mask:0xf
	v_add_f32_dpp v246, v238, v238 row_ror:8 row_mask:0xf bank_mask:0xf
	v_cndmask_b32_e64 v247, v243, v244, s[62:63]
	v_add_u32_e32 v249, 0x5000, v232
	v_cndmask_b32_e64 v248, v245, v246, s[62:63]
	v_add_u32_e32 v250, 0x5800, v232
	global_store_dword v249, v247, s[48:49]
	global_store_dword v250, v248, s[48:49]
	v_readlane_b32 s50, v254, 9
	v_readlane_b32 s51, v254, 10
	v_readlane_b32 s52, v254, 11
	v_readlane_b32 s53, v254, 12
	v_readlane_b32 s54, v254, 13
	v_readlane_b32 s55, v254, 14
	v_readlane_b32 s56, v254, 15
	v_readlane_b32 s57, v254, 16
	v_readlane_b32 s58, v254, 17
	v_readlane_b32 s59, v254, 18
	v_readlane_b32 s60, v254, 19
	v_readlane_b32 s61, v254, 20
	v_readlane_b32 s62, v254, 21
	v_readlane_b32 s63, v254, 22
	s_mov_b64 s[46:47], -1
	s_cbranch_vccnz .LBB0_183
	s_andn2_b64 vcc, exec, s[26:27]
	s_cbranch_vccnz .LBB0_182
	s_barrier
	s_branch .LBB0_182

; __device__ __forceinline__ void xcd_barrier(const XcdBarrier& b) {
;     asm volatile("s_waitcnt vmcnt(0)" ::: "memory");
;     __syncthreads();
;     if (threadIdx.x == 0) {
;         unsigned* bar = b.bar;
;         __builtin_amdgcn_s_waitcnt(0);
;         unsigned nloc = b.st[0], nx = b.st[1];
;         if (nloc == 0u) { xcd_barrier_complete(bar, b.x, nloc, nx); b.st[0] = nloc; b.st[1] = nx; }
.LBB0_202:
	v_readlane_b32 s0, v254, 0
	v_readlane_b32 s1, v254, 1
	s_cmp_gt_u32 s1, 3
	s_cselect_b64 s[0:1], -1, 0
	s_and_b64 s[0:1], s[6:7], s[0:1]
	s_andn2_b64 vcc, exec, s[0:1]
	s_cbranch_vccnz .LBB0_252
	s_waitcnt vmcnt(0)
	v_cmp_eq_u32_e32 vcc, 0, v189
	s_waitcnt vmcnt(8)
	s_barrier
	s_and_saveexec_b64 s[0:1], vcc
	s_cbranch_execz .LBB0_251
	v_mov_b32_e32 v0, 0x20430
	ds_read_b32 v0, v0
	s_waitcnt lgkmcnt(0)
	v_cmp_ne_u32_e32 vcc, 0, v0
	s_cbranch_vccz .Lseam_slow_2
	v_readlane_b32 s8, v255, 0
	v_readlane_b32 s2, v254, 4
	v_readlane_b32 s3, v254, 5
	s_and_b32 s8, s8, 63
	s_lshl_b32 s8, s8, 2
	s_add_i32 s8, s8, 0x100
	v_mov_b32_e32 v0, s8
	v_mov_b32_e32 v1, 1
	s_mov_b32 s9, 0
	s_nop 2
	global_atomic_add v0, v1, s[2:3]
.Lseam_spin_2:
	global_load_dword v2, v0, s[2:3] sc1
	s_add_i32 s9, s9, 1
	s_waitcnt vmcnt(0)
	v_cmp_gt_u32_e32 vcc, 8, v2
	s_cbranch_vccz .Lseam_done_2
	s_cmp_gt_u32 s9, 30000
	s_cbranch_scc1 .Lseam_done_2
	s_sleep 1
	s_branch .Lseam_spin_2

; __device__ __forceinline__ unsigned xb_ld(unsigned* p)              { return __hip_atomic_load(p, __ATOMIC_RELAXED, __HIP_MEMORY_SCOPE_AGENT); }
; __device__ __forceinline__ void xcd_barrier_complete(unsigned* bar, unsigned x, unsigned& nloc, unsigned& nx) {
;     const unsigned G = gridDim.x * gridDim.y * gridDim.z;
;     unsigned sum, cnt, mine, sp = 0u;
;     for (;;) {
;         sum = 0u; cnt = 0u; mine = 0u;
; #pragma unroll
;         for (unsigned j = 0; j < 16; ++j) { const unsigned c = xb_ld(&bar[XB_XCNT(j)]); sum += c; cnt += (c > 0u) ? 1u : 0u; mine = (j == x) ? c : mine; }
;         if (sum == G) break;
; __device__ __forceinline__ void xcd_barrier(const XcdBarrier& b) {
;     ...
;         unsigned nloc = b.st[0], nx = b.st[1];
;         if (nloc == 0u) { xcd_barrier_complete(bar, b.x, nloc, nx); b.st[0] = nloc; b.st[1] = nx; }
.Lseam_slow_2:
	s_add_i32 s2, 0, 0x20420
	v_mov_b32_e32 v0, s2
	s_waitcnt vmcnt(0) expcnt(0) lgkmcnt(0)
	ds_read_b32 v2, v0
	s_add_i32 s2, 0, 0x20424
	v_mov_b32_e32 v0, s2
	ds_read_b32 v0, v0
	s_waitcnt lgkmcnt(1)
	v_cmp_ne_u32_e32 vcc, 0, v2
	s_cbranch_vccnz .LBB0_219
	v_readlane_b32 s4, v254, 2
	v_readlane_b32 s5, v254, 3
	s_load_dwordx2 s[2:3], s[4:5], 0x4
	s_add_u32 s4, s90, 0x2c0200
	s_addc_u32 s5, s91, 0
	s_add_u32 s6, s90, 0x2c0400
	s_addc_u32 s7, s91, 0
	s_add_u32 s26, s90, 0x2c0500
	s_addc_u32 s27, s91, 0
	s_add_u32 s30, s90, 0x2c0600
	s_addc_u32 s31, s91, 0
	s_add_u32 s36, s90, 0x2c0700
	s_addc_u32 s37, s91, 0
	s_add_u32 s38, s90, 0x2c0800
	s_addc_u32 s39, s91, 0
	s_add_u32 s42, s90, 0x2c0900
	s_addc_u32 s43, s91, 0
	s_add_u32 s44, s90, 0x2c0a00
	s_addc_u32 s45, s91, 0
	s_add_u32 s46, s90, 0x2c0b00
	s_addc_u32 s47, s91, 0
	s_add_u32 s64, s90, 0x2c0c00
	s_addc_u32 s65, s91, 0
	s_add_u32 s72, s90, 0x2c0d00
	s_addc_u32 s73, s91, 0
	s_add_u32 s74, s90, 0x2c0e00
	s_addc_u32 s75, s91, 0
	s_add_u32 s80, s90, 0x2c0f00
	s_addc_u32 s81, s91, 0
	s_add_u32 s82, s90, 0x2c1000
	s_addc_u32 s83, s91, 0
	s_add_u32 s84, s90, 0x2c1100
	s_addc_u32 s85, s91, 0
	s_add_u32 s86, s90, 0x2c1200
	s_addc_u32 s87, s91, 0
	s_waitcnt lgkmcnt(0)
	s_mul_i32 s2, s2, s67
	s_add_u32 s88, s90, 0x2c1300
	s_mul_i32 s2, s2, s3
	s_addc_u32 s89, s91, 0
	s_mov_b32 s3, 1
	v_mov_b32_e32 v16, 0
	s_branch .LBB0_207

; __device__ __forceinline__ void xcd_barrier(const XcdBarrier& b) {
;     asm volatile("s_waitcnt vmcnt(0)" ::: "memory");
;     __syncthreads();
;     if (threadIdx.x == 0) {
;         unsigned* bar = b.bar;
;         __builtin_amdgcn_s_waitcnt(0);
;         unsigned nloc = b.st[0], nx = b.st[1];
;         if (nloc == 0u) { xcd_barrier_complete(bar, b.x, nloc, nx); b.st[0] = nloc; b.st[1] = nx; }
.LBB0_513:
	s_cmp_gt_i32 s75, 7
	s_cselect_b64 s[0:1], -1, 0
	s_and_b64 s[2:3], s[8:9], s[0:1]
	s_andn2_b64 vcc, exec, s[2:3]
	s_cbranch_vccnz .LBB0_563
	s_waitcnt vmcnt(0)
	v_cmp_eq_u32_e32 vcc, 0, v189
	s_waitcnt vmcnt(0) lgkmcnt(0)
	s_barrier
	s_and_saveexec_b64 s[4:5], vcc
	s_cbranch_execz .LBB0_562
	v_mov_b32_e32 v0, 0x20430
	ds_read_b32 v0, v0
	s_waitcnt lgkmcnt(0)
	v_cmp_ne_u32_e32 vcc, 0, v0
	s_cbranch_vccz .Lseam_slow_5
	v_readlane_b32 s8, v255, 0
	v_readlane_b32 s2, v254, 4
	v_readlane_b32 s3, v254, 5
	s_and_b32 s8, s8, 63
	s_lshl_b32 s8, s8, 2
	s_add_i32 s8, s8, 0x100
	v_mov_b32_e32 v0, s8
	v_mov_b32_e32 v1, 1
	s_mov_b32 s9, 0
	s_nop 2
	global_atomic_add v0, v1, s[2:3]
.Lseam_spin_5:
	global_load_dword v2, v0, s[2:3] sc1
	s_add_i32 s9, s9, 1
	s_waitcnt vmcnt(0)
	v_cmp_gt_u32_e32 vcc, 12, v2
	s_cbranch_vccz .Lseam_done_5
	s_cmp_gt_u32 s9, 30000
	s_cbranch_scc1 .Lseam_done_5
	s_sleep 1
	s_branch .Lseam_spin_5

; __device__ __forceinline__ unsigned xb_ld(unsigned* p)              { return __hip_atomic_load(p, __ATOMIC_RELAXED, __HIP_MEMORY_SCOPE_AGENT); }
; __device__ __forceinline__ void xcd_barrier_complete(unsigned* bar, unsigned x, unsigned& nloc, unsigned& nx) {
;     const unsigned G = gridDim.x * gridDim.y * gridDim.z;
;     unsigned sum, cnt, mine, sp = 0u;
;     for (;;) {
;         sum = 0u; cnt = 0u; mine = 0u;
; #pragma unroll
;         for (unsigned j = 0; j < 16; ++j) { const unsigned c = xb_ld(&bar[XB_XCNT(j)]); sum += c; cnt += (c > 0u) ? 1u : 0u; mine = (j == x) ? c : mine; }
;         if (sum == G) break;
; __device__ __forceinline__ void xcd_barrier(const XcdBarrier& b) {
;     ...
;         unsigned nloc = b.st[0], nx = b.st[1];
;         if (nloc == 0u) { xcd_barrier_complete(bar, b.x, nloc, nx); b.st[0] = nloc; b.st[1] = nx; }
.Lseam_slow_5:
	s_add_i32 s2, 0, 0x20420
	v_mov_b32_e32 v0, s2
	s_waitcnt vmcnt(0) expcnt(0) lgkmcnt(0)
	ds_read_b32 v2, v0
	s_add_i32 s2, 0, 0x20424
	v_mov_b32_e32 v0, s2
	ds_read_b32 v0, v0
	s_waitcnt lgkmcnt(1)
	v_cmp_ne_u32_e32 vcc, 0, v2
	s_cbranch_vccnz .LBB0_530
	v_readlane_b32 s6, v254, 2
	v_readlane_b32 s7, v254, 3
	s_load_dwordx2 s[2:3], s[6:7], 0x4
	s_add_u32 s6, s90, 0x2c0200
	s_addc_u32 s7, s91, 0
	s_add_u32 s8, s90, 0x2c0400
	s_addc_u32 s9, s91, 0
	s_add_u32 s10, s90, 0x2c0500
	s_addc_u32 s11, s91, 0
	s_add_u32 s12, s90, 0x2c0600
	s_addc_u32 s13, s91, 0
	s_add_u32 s14, s90, 0x2c0700
	s_addc_u32 s15, s91, 0
	s_add_u32 s16, s90, 0x2c0800
	s_addc_u32 s17, s91, 0
	s_add_u32 s26, s90, 0x2c0900
	s_addc_u32 s27, s91, 0
	s_add_u32 s30, s90, 0x2c0a00
	s_addc_u32 s31, s91, 0
	s_add_u32 s36, s90, 0x2c0b00
	s_addc_u32 s37, s91, 0
	s_add_u32 s38, s90, 0x2c0c00
	s_addc_u32 s39, s91, 0
	s_add_u32 s42, s90, 0x2c0d00
	s_addc_u32 s43, s91, 0
	s_add_u32 s44, s90, 0x2c0e00
	s_addc_u32 s45, s91, 0
	s_add_u32 s46, s90, 0x2c0f00
	s_addc_u32 s47, s91, 0
	s_add_u32 s50, s90, 0x2c1000
	s_addc_u32 s51, s91, 0
	s_add_u32 s52, s90, 0x2c1100
	s_addc_u32 s53, s91, 0
	s_add_u32 s54, s90, 0x2c1200
	s_addc_u32 s55, s91, 0
	s_waitcnt lgkmcnt(0)
	s_mul_i32 s2, s2, s67
	s_add_u32 s58, s90, 0x2c1300
	s_mul_i32 s2, s2, s3
	s_addc_u32 s59, s91, 0
	s_mov_b32 s3, 1
	v_mov_b32_e32 v16, 0
	s_branch .LBB0_518

;     __device__ __forceinline__ void operator()(const f32x4 (&acc)[2][2][4][2], const Unit& u, int wr, int wc, int fr, int fq) const {
;         int row0 = u.pm * BM + wr * 64 + fr, col0 = u.pn * BM + wc * 32 + 4 * fq;
;         asm volatile("" : "+v"(row0), "+v"(col0));
;         f32x4 b[2][2][2][2];
; #pragma unroll
;         for (int ch = 0; ch <= 4; ++ch) {
;             if (ch < 4) {
; #pragma unroll
;                 for (int mm = 0; mm < 2; ++mm) { const size_t off = (size_t)(row0 + (ch >> 1) * HALF + ((ch & 1) * 2 + mm) * 16) * ldc + col0;
; #pragma unroll
;                     for (int bj = 0; bj < 2; ++bj)
; #pragma unroll
;                         for (int n = 0; n < 2; ++n) b[ch & 1][mm][bj][n] = *(const f32x4*)(base + off + bj * HALF + n * 16); }
.LBB0_584:
	v_readlane_b32 s44, v254, 44
	v_readlane_b32 s45, v254, 45
	v_readlane_b32 s46, v255, 10
	v_readlane_b32 s47, v255, 11
	s_andn2_b64 vcc, exec, s[0:1]
	s_mov_b64 s[0:1], -1
	v_bfe_u32 v227, v199, 3, 1
	v_and_b32_e32 v228, 0x77, v199
	v_lshl_add_u32 v229, v227, 4, v200
	v_lshl_add_u32 v225, s42, 8, v228
	v_lshl_or_b32 v226, s55, 8, v229
	v_lshlrev_b32_e32 v224, 13, v225
	v_lshl_add_u32 v224, v226, 2, v224
	v_xor_b32_e32 v230, 16, v188
	v_xor_b32_e32 v231, 32, v188
	v_lshlrev_b32_e32 v230, 2, v230
	v_lshlrev_b32_e32 v231, 2, v231
	v_cmp_ne_u32_e64 s[6:7], 0, v227
	v_lshl_add_u32 v232, s42, 8, v199
	v_lshlrev_b32_e32 v232, 7, v232
	v_bfe_u32 v233, v200, 5, 2
	v_lshl_add_u32 v233, s55, 2, v233
	v_lshl_add_u32 v232, v233, 2, v232
	v_lshrrev_b32_e32 v234, 1, v224
	s_nop 7
	v_mov_b32_e32 v244, v120
	v_mov_b32_e32 v245, v121
	v_mov_b32_e32 v246, v122
	v_mov_b32_e32 v247, v123
	v_mov_b32_dpp v120, v124 row_ror:8 row_mask:0xf bank_mask:0x3
	v_mov_b32_dpp v121, v125 row_ror:8 row_mask:0xf bank_mask:0x3
	v_mov_b32_dpp v122, v126 row_ror:8 row_mask:0xf bank_mask:0x3
	v_mov_b32_dpp v123, v127 row_ror:8 row_mask:0xf bank_mask:0x3
	v_mov_b32_dpp v124, v244 row_ror:8 row_mask:0xf bank_mask:0xc
	v_mov_b32_dpp v125, v245 row_ror:8 row_mask:0xf bank_mask:0xc
	v_mov_b32_dpp v126, v246 row_ror:8 row_mask:0xf bank_mask:0xc
	v_mov_b32_dpp v127, v247 row_ror:8 row_mask:0xf bank_mask:0xc
	v_mov_b32_e32 v244, v112
	v_mov_b32_e32 v245, v113
	v_mov_b32_e32 v246, v114
	v_mov_b32_e32 v247, v115
	v_mov_b32_dpp v112, v116 row_ror:8 row_mask:0xf bank_mask:0x3
	v_mov_b32_dpp v113, v117 row_ror:8 row_mask:0xf bank_mask:0x3
	v_mov_b32_dpp v114, v118 row_ror:8 row_mask:0xf bank_mask:0x3
	v_mov_b32_dpp v115, v119 row_ror:8 row_mask:0xf bank_mask:0x3
	v_mov_b32_dpp v116, v244 row_ror:8 row_mask:0xf bank_mask:0xc
	v_mov_b32_dpp v117, v245 row_ror:8 row_mask:0xf bank_mask:0xc
	v_mov_b32_dpp v118, v246 row_ror:8 row_mask:0xf bank_mask:0xc
	v_mov_b32_dpp v119, v247 row_ror:8 row_mask:0xf bank_mask:0xc
	v_mov_b32_e32 v244, v104
	v_mov_b32_e32 v245, v105
	v_mov_b32_e32 v246, v106
	v_mov_b32_e32 v247, v107
	v_mov_b32_dpp v104, v108 row_ror:8 row_mask:0xf bank_mask:0x3
	v_mov_b32_dpp v105, v109 row_ror:8 row_mask:0xf bank_mask:0x3
	v_mov_b32_dpp v106, v110 row_ror:8 row_mask:0xf bank_mask:0x3
	v_mov_b32_dpp v107, v111 row_ror:8 row_mask:0xf bank_mask:0x3
	v_mov_b32_dpp v108, v244 row_ror:8 row_mask:0xf bank_mask:0xc
	v_mov_b32_dpp v109, v245 row_ror:8 row_mask:0xf bank_mask:0xc
	v_mov_b32_dpp v110, v246 row_ror:8 row_mask:0xf bank_mask:0xc
	v_mov_b32_dpp v111, v247 row_ror:8 row_mask:0xf bank_mask:0xc
	v_mov_b32_e32 v244, v96
	v_mov_b32_e32 v245, v97
	v_mov_b32_e32 v246, v98
	v_mov_b32_e32 v247, v99
	v_mov_b32_dpp v96, v100 row_ror:8 row_mask:0xf bank_mask:0x3
	v_mov_b32_dpp v97, v101 row_ror:8 row_mask:0xf bank_mask:0x3
	v_mov_b32_dpp v98, v102 row_ror:8 row_mask:0xf bank_mask:0x3
	v_mov_b32_dpp v99, v103 row_ror:8 row_mask:0xf bank_mask:0x3
	v_mov_b32_dpp v100, v244 row_ror:8 row_mask:0xf bank_mask:0xc
	v_mov_b32_dpp v101, v245 row_ror:8 row_mask:0xf bank_mask:0xc
	v_mov_b32_dpp v102, v246 row_ror:8 row_mask:0xf bank_mask:0xc
	v_mov_b32_dpp v103, v247 row_ror:8 row_mask:0xf bank_mask:0xc
	v_mov_b32_e32 v244, v88
	v_mov_b32_e32 v245, v89
	v_mov_b32_e32 v246, v90
	v_mov_b32_e32 v247, v91
	v_mov_b32_dpp v88, v92 row_ror:8 row_mask:0xf bank_mask:0x3
	v_mov_b32_dpp v89, v93 row_ror:8 row_mask:0xf bank_mask:0x3
	v_mov_b32_dpp v90, v94 row_ror:8 row_mask:0xf bank_mask:0x3
	v_mov_b32_dpp v91, v95 row_ror:8 row_mask:0xf bank_mask:0x3
	v_mov_b32_dpp v92, v244 row_ror:8 row_mask:0xf bank_mask:0xc
	v_mov_b32_dpp v93, v245 row_ror:8 row_mask:0xf bank_mask:0xc
	v_mov_b32_dpp v94, v246 row_ror:8 row_mask:0xf bank_mask:0xc
	v_mov_b32_dpp v95, v247 row_ror:8 row_mask:0xf bank_mask:0xc
	v_mov_b32_e32 v244, v80
	v_mov_b32_e32 v245, v81
	v_mov_b32_e32 v246, v82
	v_mov_b32_e32 v247, v83
	v_mov_b32_dpp v80, v84 row_ror:8 row_mask:0xf bank_mask:0x3
	v_mov_b32_dpp v81, v85 row_ror:8 row_mask:0xf bank_mask:0x3
	v_mov_b32_dpp v82, v86 row_ror:8 row_mask:0xf bank_mask:0x3
	v_mov_b32_dpp v83, v87 row_ror:8 row_mask:0xf bank_mask:0x3
	v_mov_b32_dpp v84, v244 row_ror:8 row_mask:0xf bank_mask:0xc
	v_mov_b32_dpp v85, v245 row_ror:8 row_mask:0xf bank_mask:0xc
	v_mov_b32_dpp v86, v246 row_ror:8 row_mask:0xf bank_mask:0xc
	v_mov_b32_dpp v87, v247 row_ror:8 row_mask:0xf bank_mask:0xc
	v_mov_b32_e32 v244, v72
	v_mov_b32_e32 v245, v73
	v_mov_b32_e32 v246, v74
	v_mov_b32_e32 v247, v75
	v_mov_b32_dpp v72, v76 row_ror:8 row_mask:0xf bank_mask:0x3
	v_mov_b32_dpp v73, v77 row_ror:8 row_mask:0xf bank_mask:0x3
	v_mov_b32_dpp v74, v78 row_ror:8 row_mask:0xf bank_mask:0x3
	v_mov_b32_dpp v75, v79 row_ror:8 row_mask:0xf bank_mask:0x3
	v_mov_b32_dpp v76, v244 row_ror:8 row_mask:0xf bank_mask:0xc
	v_mov_b32_dpp v77, v245 row_ror:8 row_mask:0xf bank_mask:0xc
	v_mov_b32_dpp v78, v246 row_ror:8 row_mask:0xf bank_mask:0xc
	v_mov_b32_dpp v79, v247 row_ror:8 row_mask:0xf bank_mask:0xc
	v_mov_b32_e32 v244, v64
	v_mov_b32_e32 v245, v65
	v_mov_b32_e32 v246, v66
	v_mov_b32_e32 v247, v67
	v_mov_b32_dpp v64, v68 row_ror:8 row_mask:0xf bank_mask:0x3
	v_mov_b32_dpp v65, v69 row_ror:8 row_mask:0xf bank_mask:0x3
	v_mov_b32_dpp v66, v70 row_ror:8 row_mask:0xf bank_mask:0x3
	v_mov_b32_dpp v67, v71 row_ror:8 row_mask:0xf bank_mask:0x3
	v_mov_b32_dpp v68, v244 row_ror:8 row_mask:0xf bank_mask:0xc
	v_mov_b32_dpp v69, v245 row_ror:8 row_mask:0xf bank_mask:0xc
	v_mov_b32_dpp v70, v246 row_ror:8 row_mask:0xf bank_mask:0xc
	v_mov_b32_dpp v71, v247 row_ror:8 row_mask:0xf bank_mask:0xc
	v_mov_b32_e32 v244, v56
	v_mov_b32_e32 v245, v57
;     __device__ __forceinline__ void operator()(const f32x4 (&acc)[2][2][4][2], const Unit& u, int wr, int wc, int fr, int fq) const {
;     ...
;         for (int ch = 0; ch <= 4; ++ch) {
;             if (ch < 4) {
; #pragma unroll
;                 for (int mm = 0; mm < 2; ++mm) { const size_t off = (size_t)(row0 + (ch >> 1) * HALF + ((ch & 1) * 2 + mm) * 16) * ldc + col0;
; #pragma unroll
;                     for (int bj = 0; bj < 2; ++bj)
; #pragma unroll
;                         for (int n = 0; n < 2; ++n) b[ch & 1][mm][bj][n] = *(const f32x4*)(base + off + bj * HALF + n * 16); }
	v_mov_b32_e32 v246, v58
	v_mov_b32_e32 v247, v59
	v_mov_b32_dpp v56, v60 row_ror:8 row_mask:0xf bank_mask:0x3
	v_mov_b32_dpp v57, v61 row_ror:8 row_mask:0xf bank_mask:0x3
	v_mov_b32_dpp v58, v62 row_ror:8 row_mask:0xf bank_mask:0x3
	v_mov_b32_dpp v59, v63 row_ror:8 row_mask:0xf bank_mask:0x3
	v_mov_b32_dpp v60, v244 row_ror:8 row_mask:0xf bank_mask:0xc
	v_mov_b32_dpp v61, v245 row_ror:8 row_mask:0xf bank_mask:0xc
	v_mov_b32_dpp v62, v246 row_ror:8 row_mask:0xf bank_mask:0xc
	v_mov_b32_dpp v63, v247 row_ror:8 row_mask:0xf bank_mask:0xc
	v_mov_b32_e32 v244, v48
	v_mov_b32_e32 v245, v49
	v_mov_b32_e32 v246, v50
	v_mov_b32_e32 v247, v51
	v_mov_b32_dpp v48, v52 row_ror:8 row_mask:0xf bank_mask:0x3
	v_mov_b32_dpp v49, v53 row_ror:8 row_mask:0xf bank_mask:0x3
	v_mov_b32_dpp v50, v54 row_ror:8 row_mask:0xf bank_mask:0x3
	v_mov_b32_dpp v51, v55 row_ror:8 row_mask:0xf bank_mask:0x3
	v_mov_b32_dpp v52, v244 row_ror:8 row_mask:0xf bank_mask:0xc
	v_mov_b32_dpp v53, v245 row_ror:8 row_mask:0xf bank_mask:0xc
	v_mov_b32_dpp v54, v246 row_ror:8 row_mask:0xf bank_mask:0xc
	v_mov_b32_dpp v55, v247 row_ror:8 row_mask:0xf bank_mask:0xc
	v_mov_b32_e32 v244, v40
	v_mov_b32_e32 v245, v41
	v_mov_b32_e32 v246, v42
	v_mov_b32_e32 v247, v43
	v_mov_b32_dpp v40, v44 row_ror:8 row_mask:0xf bank_mask:0x3
	v_mov_b32_dpp v41, v45 row_ror:8 row_mask:0xf bank_mask:0x3
	v_mov_b32_dpp v42, v46 row_ror:8 row_mask:0xf bank_mask:0x3
	v_mov_b32_dpp v43, v47 row_ror:8 row_mask:0xf bank_mask:0x3
	v_mov_b32_dpp v44, v244 row_ror:8 row_mask:0xf bank_mask:0xc
	v_mov_b32_dpp v45, v245 row_ror:8 row_mask:0xf bank_mask:0xc
	v_mov_b32_dpp v46, v246 row_ror:8 row_mask:0xf bank_mask:0xc
	v_mov_b32_dpp v47, v247 row_ror:8 row_mask:0xf bank_mask:0xc
	v_mov_b32_e32 v244, v32
	v_mov_b32_e32 v245, v33
	v_mov_b32_e32 v246, v34
	v_mov_b32_e32 v247, v35
	v_mov_b32_dpp v32, v36 row_ror:8 row_mask:0xf bank_mask:0x3
	v_mov_b32_dpp v33, v37 row_ror:8 row_mask:0xf bank_mask:0x3
	v_mov_b32_dpp v34, v38 row_ror:8 row_mask:0xf bank_mask:0x3
	v_mov_b32_dpp v35, v39 row_ror:8 row_mask:0xf bank_mask:0x3
	v_mov_b32_dpp v36, v244 row_ror:8 row_mask:0xf bank_mask:0xc
	v_mov_b32_dpp v37, v245 row_ror:8 row_mask:0xf bank_mask:0xc
	v_mov_b32_dpp v38, v246 row_ror:8 row_mask:0xf bank_mask:0xc
	v_mov_b32_dpp v39, v247 row_ror:8 row_mask:0xf bank_mask:0xc
	v_mov_b32_e32 v244, v24
	v_mov_b32_e32 v245, v25
	v_mov_b32_e32 v246, v26
	v_mov_b32_e32 v247, v27
	v_mov_b32_dpp v24, v28 row_ror:8 row_mask:0xf bank_mask:0x3
	v_mov_b32_dpp v25, v29 row_ror:8 row_mask:0xf bank_mask:0x3
	v_mov_b32_dpp v26, v30 row_ror:8 row_mask:0xf bank_mask:0x3
	v_mov_b32_dpp v27, v31 row_ror:8 row_mask:0xf bank_mask:0x3
	v_mov_b32_dpp v28, v244 row_ror:8 row_mask:0xf bank_mask:0xc
	v_mov_b32_dpp v29, v245 row_ror:8 row_mask:0xf bank_mask:0xc
	v_mov_b32_dpp v30, v246 row_ror:8 row_mask:0xf bank_mask:0xc
	v_mov_b32_dpp v31, v247 row_ror:8 row_mask:0xf bank_mask:0xc
	v_mov_b32_e32 v244, v16
	v_mov_b32_e32 v245, v17
	v_mov_b32_e32 v246, v18
	v_mov_b32_e32 v247, v19
	v_mov_b32_dpp v16, v20 row_ror:8 row_mask:0xf bank_mask:0x3
	v_mov_b32_dpp v17, v21 row_ror:8 row_mask:0xf bank_mask:0x3
	v_mov_b32_dpp v18, v22 row_ror:8 row_mask:0xf bank_mask:0x3
	v_mov_b32_dpp v19, v23 row_ror:8 row_mask:0xf bank_mask:0x3
	v_mov_b32_dpp v20, v244 row_ror:8 row_mask:0xf bank_mask:0xc
	v_mov_b32_dpp v21, v245 row_ror:8 row_mask:0xf bank_mask:0xc
	v_mov_b32_dpp v22, v246 row_ror:8 row_mask:0xf bank_mask:0xc
	v_mov_b32_dpp v23, v247 row_ror:8 row_mask:0xf bank_mask:0xc
	v_mov_b32_e32 v244, v8
	v_mov_b32_e32 v245, v9
	v_mov_b32_e32 v246, v10
	v_mov_b32_e32 v247, v11
	v_mov_b32_dpp v8, v12 row_ror:8 row_mask:0xf bank_mask:0x3
	v_mov_b32_dpp v9, v13 row_ror:8 row_mask:0xf bank_mask:0x3
	v_mov_b32_dpp v10, v14 row_ror:8 row_mask:0xf bank_mask:0x3
	v_mov_b32_dpp v11, v15 row_ror:8 row_mask:0xf bank_mask:0x3
	v_mov_b32_dpp v12, v244 row_ror:8 row_mask:0xf bank_mask:0xc
	v_mov_b32_dpp v13, v245 row_ror:8 row_mask:0xf bank_mask:0xc
	v_mov_b32_dpp v14, v246 row_ror:8 row_mask:0xf bank_mask:0xc
	v_mov_b32_dpp v15, v247 row_ror:8 row_mask:0xf bank_mask:0xc
	v_mov_b32_e32 v244, v0
	v_mov_b32_e32 v245, v1
	v_mov_b32_e32 v246, v2
	v_mov_b32_e32 v247, v3
	v_mov_b32_dpp v0, v4 row_ror:8 row_mask:0xf bank_mask:0x3
	v_mov_b32_dpp v1, v5 row_ror:8 row_mask:0xf bank_mask:0x3
	v_mov_b32_dpp v2, v6 row_ror:8 row_mask:0xf bank_mask:0x3
	v_mov_b32_dpp v3, v7 row_ror:8 row_mask:0xf bank_mask:0x3
	v_mov_b32_dpp v4, v244 row_ror:8 row_mask:0xf bank_mask:0xc
	v_mov_b32_dpp v5, v245 row_ror:8 row_mask:0xf bank_mask:0xc
	v_mov_b32_dpp v6, v246 row_ror:8 row_mask:0xf bank_mask:0xc
	v_mov_b32_dpp v7, v247 row_ror:8 row_mask:0xf bank_mask:0xc
	v_add_u32_e32 v216, 0x0, v224
	v_add_u32_e32 v217, 0x10000, v224
	v_add_u32_e32 v218, 0x20000, v224
	v_add_u32_e32 v219, 0x30000, v224
	global_load_dwordx4 v[128:131], v216, s[88:89]
	global_load_dwordx4 v[132:135], v216, s[88:89] offset:512
	global_load_dwordx4 v[136:139], v217, s[88:89]
	global_load_dwordx4 v[140:143], v217, s[88:89] offset:512
	global_load_dwordx4 v[144:147], v218, s[88:89]
	global_load_dwordx4 v[148:151], v218, s[88:89] offset:512
	global_load_dwordx4 v[152:155], v219, s[88:89]
	global_load_dwordx4 v[156:159], v219, s[88:89] offset:512
	v_add_u32_e32 v220, 0x40000, v224
	v_add_u32_e32 v221, 0x50000, v224
	v_add_u32_e32 v222, 0x60000, v224
	v_add_u32_e32 v223, 0x70000, v224
	global_load_dwordx4 v[164:167], v220, s[88:89]
	global_load_dwordx4 v[168:171], v220, s[88:89] offset:512
	global_load_dwordx4 v[172:175], v221, s[88:89]
	global_load_dwordx4 v[176:179], v221, s[88:89] offset:512
	global_load_dwordx4 v[180:183], v222, s[88:89]
	global_load_dwordx4 v[184:187], v222, s[88:89] offset:512
	global_load_dwordx4 v[208:211], v223, s[88:89]
	global_load_dwordx4 v[212:215], v223, s[88:89] offset:512
	s_waitcnt vmcnt(8)
; __device__ __forceinline__ unsigned cvt_pk_bf16(float lo, float hi) { typedef float f2_t __attribute__((ext_vector_type(2))); typedef __bf16 b2_t __attribute__((ext_vector_type(2))); const f2_t v = {lo, hi}; return __builtin_bit_cast(unsigned, __builtin_convertvector(v, b2_t)); }
;     __device__ __forceinline__ void operator()(const f32x4 (&acc)[2][2][4][2], const Unit& u, int wr, int wc, int fr, int fq) const {
;     ...
;             if (ch > 0) {
;                 const int pc = ch - 1, ai = pc >> 1;
; #pragma unroll
;                 for (int mm = 0; mm < 2; ++mm) { const int m = (pc & 1) * 2 + mm, row = row0 + ai * HALF + m * 16; const size_t off = (size_t)row * ldc + col0;
;                     float s = 0.f;
; #pragma unroll
;                     for (int bj = 0; bj < 2; ++bj)
; #pragma unroll
;                         for (int n = 0; n < 2; ++n) {
;                             const f32x4 o = b[pc & 1][mm][bj][n] + acc[ai][bj][m][n] * scale;
;                             *(f32x4*)(out + off + bj * HALF + n * 16) = o;
;                             if (NORM) { s += (o[0] * o[0] + o[1] * o[1]) + (o[2] * o[2] + o[3] * o[3]);
;                                 u32x2 w; w.x = cvt_pk_bf16(o[0], o[1]); w.y = cvt_pk_bf16(o[2], o[3]); *(u32x2*)(xb + off + bj * HALF + n * 16) = w; }
;                         }
;                     if (NORM) { s += __shfl_xor(s, 16); s += __shfl_xor(s, 32); ssq[(size_t)row * 32 + u.pn * 4 + wc] = s; }
;                 }
	v_pk_add_f32 v[124:125], v[124:125], v[128:129]
	v_pk_add_f32 v[126:127], v[126:127], v[130:131]
	v_pk_add_f32 v[116:117], v[116:117], v[132:133]
	v_pk_add_f32 v[118:119], v[118:119], v[134:135]
	v_pk_add_f32 v[120:121], v[120:121], v[136:137]
	v_pk_add_f32 v[122:123], v[122:123], v[138:139]
	v_pk_add_f32 v[112:113], v[112:113], v[140:141]
	v_pk_add_f32 v[114:115], v[114:115], v[142:143]
	v_pk_add_f32 v[108:109], v[108:109], v[144:145]
	v_pk_add_f32 v[110:111], v[110:111], v[146:147]
	v_pk_add_f32 v[100:101], v[100:101], v[148:149]
	v_pk_add_f32 v[102:103], v[102:103], v[150:151]
	v_pk_add_f32 v[104:105], v[104:105], v[152:153]
	v_pk_add_f32 v[106:107], v[106:107], v[154:155]
	v_pk_add_f32 v[96:97], v[96:97], v[156:157]
	v_pk_add_f32 v[98:99], v[98:99], v[158:159]
	global_store_dwordx4 v216, v[124:127], s[88:89]
	global_store_dwordx4 v216, v[116:119], s[88:89] offset:512
	global_store_dwordx4 v217, v[120:123], s[88:89]
	global_store_dwordx4 v217, v[112:115], s[88:89] offset:512
	global_store_dwordx4 v218, v[108:111], s[88:89]
	global_store_dwordx4 v218, v[100:103], s[88:89] offset:512
	global_store_dwordx4 v219, v[104:107], s[88:89]
	global_store_dwordx4 v219, v[96:99], s[88:89] offset:512
	v_mul_f32_e32 v235, v124, v124
	v_fmac_f32_e32 v235, v125, v125
	v_fmac_f32_e32 v235, v126, v126
	v_fmac_f32_e32 v235, v127, v127
	v_fmac_f32_e32 v235, v116, v116
	v_fmac_f32_e32 v235, v117, v117
	v_fmac_f32_e32 v235, v118, v118
	v_fmac_f32_e32 v235, v119, v119
	v_mul_f32_e32 v236, v120, v120
	v_fmac_f32_e32 v236, v121, v121
	v_fmac_f32_e32 v236, v122, v122
	v_fmac_f32_e32 v236, v123, v123
	v_fmac_f32_e32 v236, v112, v112
	v_fmac_f32_e32 v236, v113, v113
	v_fmac_f32_e32 v236, v114, v114
	v_fmac_f32_e32 v236, v115, v115
	v_mul_f32_e32 v237, v108, v108
	v_fmac_f32_e32 v237, v109, v109
	v_fmac_f32_e32 v237, v110, v110
	v_fmac_f32_e32 v237, v111, v111
	v_fmac_f32_e32 v237, v100, v100
	v_fmac_f32_e32 v237, v101, v101
	v_fmac_f32_e32 v237, v102, v102
	v_fmac_f32_e32 v237, v103, v103
	v_mul_f32_e32 v238, v104, v104
	v_fmac_f32_e32 v238, v105, v105
	v_fmac_f32_e32 v238, v106, v106
	v_fmac_f32_e32 v238, v107, v107
	v_fmac_f32_e32 v238, v96, v96
	v_fmac_f32_e32 v238, v97, v97
	v_fmac_f32_e32 v238, v98, v98
	v_fmac_f32_e32 v238, v99, v99
	v_cvt_pk_bf16_f32 v128, v124, v125
	v_cvt_pk_bf16_f32 v129, v126, v127
	v_cvt_pk_bf16_f32 v132, v116, v117
	v_cvt_pk_bf16_f32 v133, v118, v119
	v_cvt_pk_bf16_f32 v136, v120, v121
	v_cvt_pk_bf16_f32 v137, v122, v123
	v_cvt_pk_bf16_f32 v140, v112, v113
	v_cvt_pk_bf16_f32 v141, v114, v115
	v_cvt_pk_bf16_f32 v144, v108, v109
	v_cvt_pk_bf16_f32 v145, v110, v111
	v_cvt_pk_bf16_f32 v148, v100, v101
	v_cvt_pk_bf16_f32 v149, v102, v103
	v_cvt_pk_bf16_f32 v152, v104, v105
	v_cvt_pk_bf16_f32 v153, v106, v107
	v_cvt_pk_bf16_f32 v156, v96, v97
	v_cvt_pk_bf16_f32 v157, v98, v99
	v_add_u32_e32 v239, 0x0, v234
	v_add_u32_e32 v190, 0x8000, v234
	v_add_u32_e32 v191, 0x10000, v234
	v_add_u32_e32 v192, 0x18000, v234
	global_store_dwordx2 v239, v[128:129], s[44:45]
	global_store_dwordx2 v239, v[132:133], s[44:45] offset:256
	global_store_dwordx2 v190, v[136:137], s[44:45]
	global_store_dwordx2 v190, v[140:141], s[44:45] offset:256
	global_store_dwordx2 v191, v[144:145], s[44:45]
	global_store_dwordx2 v191, v[148:149], s[44:45] offset:256
	global_store_dwordx2 v192, v[152:153], s[44:45]
	global_store_dwordx2 v192, v[156:157], s[44:45] offset:256
	ds_bpermute_b32 v193, v230, v235
	ds_bpermute_b32 v194, v230, v236
	ds_bpermute_b32 v195, v230, v237
	ds_bpermute_b32 v207, v230, v238
	s_waitcnt lgkmcnt(0)
	v_add_f32_e32 v235, v235, v193
	v_add_f32_e32 v236, v236, v194
	v_add_f32_e32 v237, v237, v195
	v_add_f32_e32 v238, v238, v207
	ds_bpermute_b32 v193, v231, v235
	ds_bpermute_b32 v194, v231, v236
	ds_bpermute_b32 v195, v231, v237
	ds_bpermute_b32 v207, v231, v238
	s_waitcnt lgkmcnt(0)
	v_add_f32_e32 v235, v235, v193
	v_add_f32_e32 v236, v236, v194
	v_add_f32_e32 v237, v237, v195
	v_add_f32_e32 v238, v238, v207
	s_nop 1
	v_add_f32_dpp v193, v235, v235 row_ror:8 row_mask:0xf bank_mask:0xf
	v_add_f32_dpp v194, v236, v236 row_ror:8 row_mask:0xf bank_mask:0xf
	v_add_f32_dpp v195, v237, v237 row_ror:8 row_mask:0xf bank_mask:0xf
	v_add_f32_dpp v207, v238, v238 row_ror:8 row_mask:0xf bank_mask:0xf
	v_cndmask_b32_e64 v248, v193, v194, s[6:7]
	v_add_u32_e32 v250, 0x0, v232
	v_cndmask_b32_e64 v249, v195, v207, s[6:7]
	v_add_u32_e32 v251, 0x800, v232
	global_store_dword v250, v248, s[46:47]
	global_store_dword v251, v249, s[46:47]
	v_add_u32_e32 v216, 0x100000, v224
	v_add_u32_e32 v217, 0x110000, v224
	v_add_u32_e32 v218, 0x120000, v224
	v_add_u32_e32 v219, 0x130000, v224
	global_load_dwordx4 v[128:131], v216, s[88:89]
	global_load_dwordx4 v[132:135], v216, s[88:89] offset:512
	global_load_dwordx4 v[136:139], v217, s[88:89]
	global_load_dwordx4 v[140:143], v217, s[88:89] offset:512
	global_load_dwordx4 v[144:147], v218, s[88:89]
	global_load_dwordx4 v[148:151], v218, s[88:89] offset:512
	global_load_dwordx4 v[152:155], v219, s[88:89]
	global_load_dwordx4 v[156:159], v219, s[88:89] offset:512
	s_waitcnt vmcnt(26)
; __device__ __forceinline__ unsigned cvt_pk_bf16(float lo, float hi) { typedef float f2_t __attribute__((ext_vector_type(2))); typedef __bf16 b2_t __attribute__((ext_vector_type(2))); const f2_t v = {lo, hi}; return __builtin_bit_cast(unsigned, __builtin_convertvector(v, b2_t)); }
;     __device__ __forceinline__ void operator()(const f32x4 (&acc)[2][2][4][2], const Unit& u, int wr, int wc, int fr, int fq) const {
;     ...
;             if (ch > 0) {
;                 const int pc = ch - 1, ai = pc >> 1;
; #pragma unroll
;                 for (int mm = 0; mm < 2; ++mm) { const int m = (pc & 1) * 2 + mm, row = row0 + ai * HALF + m * 16; const size_t off = (size_t)row * ldc + col0;
;                     float s = 0.f;
; #pragma unroll
;                     for (int bj = 0; bj < 2; ++bj)
; #pragma unroll
;                         for (int n = 0; n < 2; ++n) {
;                             const f32x4 o = b[pc & 1][mm][bj][n] + acc[ai][bj][m][n] * scale;
;                             *(f32x4*)(out + off + bj * HALF + n * 16) = o;
;                             if (NORM) { s += (o[0] * o[0] + o[1] * o[1]) + (o[2] * o[2] + o[3] * o[3]);
;                                 u32x2 w; w.x = cvt_pk_bf16(o[0], o[1]); w.y = cvt_pk_bf16(o[2], o[3]); *(u32x2*)(xb + off + bj * HALF + n * 16) = w; }
;                         }
;                     if (NORM) { s += __shfl_xor(s, 16); s += __shfl_xor(s, 32); ssq[(size_t)row * 32 + u.pn * 4 + wc] = s; }
;                 }
	v_pk_add_f32 v[92:93], v[92:93], v[164:165]
	v_pk_add_f32 v[94:95], v[94:95], v[166:167]
	v_pk_add_f32 v[84:85], v[84:85], v[168:169]
	v_pk_add_f32 v[86:87], v[86:87], v[170:171]
	v_pk_add_f32 v[88:89], v[88:89], v[172:173]
	v_pk_add_f32 v[90:91], v[90:91], v[174:175]
	v_pk_add_f32 v[80:81], v[80:81], v[176:177]
	v_pk_add_f32 v[82:83], v[82:83], v[178:179]
	v_pk_add_f32 v[76:77], v[76:77], v[180:181]
	v_pk_add_f32 v[78:79], v[78:79], v[182:183]
	v_pk_add_f32 v[68:69], v[68:69], v[184:185]
	v_pk_add_f32 v[70:71], v[70:71], v[186:187]
	v_pk_add_f32 v[72:73], v[72:73], v[208:209]
	v_pk_add_f32 v[74:75], v[74:75], v[210:211]
	v_pk_add_f32 v[64:65], v[64:65], v[212:213]
	v_pk_add_f32 v[66:67], v[66:67], v[214:215]
	global_store_dwordx4 v220, v[92:95], s[88:89]
	global_store_dwordx4 v220, v[84:87], s[88:89] offset:512
	global_store_dwordx4 v221, v[88:91], s[88:89]
	global_store_dwordx4 v221, v[80:83], s[88:89] offset:512
	global_store_dwordx4 v222, v[76:79], s[88:89]
	global_store_dwordx4 v222, v[68:71], s[88:89] offset:512
	global_store_dwordx4 v223, v[72:75], s[88:89]
	global_store_dwordx4 v223, v[64:67], s[88:89] offset:512
	v_mul_f32_e32 v235, v92, v92
	v_fmac_f32_e32 v235, v93, v93
	v_fmac_f32_e32 v235, v94, v94
	v_fmac_f32_e32 v235, v95, v95
	v_fmac_f32_e32 v235, v84, v84
	v_fmac_f32_e32 v235, v85, v85
	v_fmac_f32_e32 v235, v86, v86
	v_fmac_f32_e32 v235, v87, v87
	v_mul_f32_e32 v236, v88, v88
	v_fmac_f32_e32 v236, v89, v89
	v_fmac_f32_e32 v236, v90, v90
	v_fmac_f32_e32 v236, v91, v91
	v_fmac_f32_e32 v236, v80, v80
	v_fmac_f32_e32 v236, v81, v81
	v_fmac_f32_e32 v236, v82, v82
	v_fmac_f32_e32 v236, v83, v83
	v_mul_f32_e32 v237, v76, v76
	v_fmac_f32_e32 v237, v77, v77
	v_fmac_f32_e32 v237, v78, v78
	v_fmac_f32_e32 v237, v79, v79
	v_fmac_f32_e32 v237, v68, v68
	v_fmac_f32_e32 v237, v69, v69
	v_fmac_f32_e32 v237, v70, v70
	v_fmac_f32_e32 v237, v71, v71
	v_mul_f32_e32 v238, v72, v72
	v_fmac_f32_e32 v238, v73, v73
	v_fmac_f32_e32 v238, v74, v74
	v_fmac_f32_e32 v238, v75, v75
	v_fmac_f32_e32 v238, v64, v64
	v_fmac_f32_e32 v238, v65, v65
	v_fmac_f32_e32 v238, v66, v66
	v_fmac_f32_e32 v238, v67, v67
	v_cvt_pk_bf16_f32 v164, v92, v93
	v_cvt_pk_bf16_f32 v165, v94, v95
	v_cvt_pk_bf16_f32 v168, v84, v85
	v_cvt_pk_bf16_f32 v169, v86, v87
	v_cvt_pk_bf16_f32 v172, v88, v89
	v_cvt_pk_bf16_f32 v173, v90, v91
	v_cvt_pk_bf16_f32 v176, v80, v81
	v_cvt_pk_bf16_f32 v177, v82, v83
	v_cvt_pk_bf16_f32 v180, v76, v77
	v_cvt_pk_bf16_f32 v181, v78, v79
	v_cvt_pk_bf16_f32 v184, v68, v69
	v_cvt_pk_bf16_f32 v185, v70, v71
	v_cvt_pk_bf16_f32 v208, v72, v73
	v_cvt_pk_bf16_f32 v209, v74, v75
	v_cvt_pk_bf16_f32 v212, v64, v65
	v_cvt_pk_bf16_f32 v213, v66, v67
	v_add_u32_e32 v239, 0x20000, v234
	v_add_u32_e32 v190, 0x28000, v234
	v_add_u32_e32 v191, 0x30000, v234
	v_add_u32_e32 v192, 0x38000, v234
	global_store_dwordx2 v239, v[164:165], s[44:45]
	global_store_dwordx2 v239, v[168:169], s[44:45] offset:256
	global_store_dwordx2 v190, v[172:173], s[44:45]
	global_store_dwordx2 v190, v[176:177], s[44:45] offset:256
	global_store_dwordx2 v191, v[180:181], s[44:45]
	global_store_dwordx2 v191, v[184:185], s[44:45] offset:256
	global_store_dwordx2 v192, v[208:209], s[44:45]
	global_store_dwordx2 v192, v[212:213], s[44:45] offset:256
	ds_bpermute_b32 v193, v230, v235
	ds_bpermute_b32 v194, v230, v236
	ds_bpermute_b32 v195, v230, v237
	ds_bpermute_b32 v207, v230, v238
	s_waitcnt lgkmcnt(0)
	v_add_f32_e32 v235, v235, v193
	v_add_f32_e32 v236, v236, v194
	v_add_f32_e32 v237, v237, v195
	v_add_f32_e32 v238, v238, v207
	ds_bpermute_b32 v193, v231, v235
	ds_bpermute_b32 v194, v231, v236
	ds_bpermute_b32 v195, v231, v237
	ds_bpermute_b32 v207, v231, v238
	s_waitcnt lgkmcnt(0)
	v_add_f32_e32 v235, v235, v193
	v_add_f32_e32 v236, v236, v194
	v_add_f32_e32 v237, v237, v195
	v_add_f32_e32 v238, v238, v207
	s_nop 1
	v_add_f32_dpp v193, v235, v235 row_ror:8 row_mask:0xf bank_mask:0xf
	v_add_f32_dpp v194, v236, v236 row_ror:8 row_mask:0xf bank_mask:0xf
	v_add_f32_dpp v195, v237, v237 row_ror:8 row_mask:0xf bank_mask:0xf
	v_add_f32_dpp v207, v238, v238 row_ror:8 row_mask:0xf bank_mask:0xf
	v_cndmask_b32_e64 v248, v193, v194, s[6:7]
	v_add_u32_e32 v250, 0x1000, v232
	v_cndmask_b32_e64 v249, v195, v207, s[6:7]
	v_add_u32_e32 v251, 0x1800, v232
	global_store_dword v250, v248, s[46:47]
	global_store_dword v251, v249, s[46:47]
	v_add_u32_e32 v220, 0x140000, v224
	v_add_u32_e32 v221, 0x150000, v224
	v_add_u32_e32 v222, 0x160000, v224
	v_add_u32_e32 v223, 0x170000, v224
	global_load_dwordx4 v[164:167], v220, s[88:89]
	global_load_dwordx4 v[168:171], v220, s[88:89] offset:512
	global_load_dwordx4 v[172:175], v221, s[88:89]
	global_load_dwordx4 v[176:179], v221, s[88:89] offset:512
	global_load_dwordx4 v[180:183], v222, s[88:89]
	global_load_dwordx4 v[184:187], v222, s[88:89] offset:512
	global_load_dwordx4 v[208:211], v223, s[88:89]
	global_load_dwordx4 v[212:215], v223, s[88:89] offset:512
	s_waitcnt vmcnt(26)
; __device__ __forceinline__ unsigned cvt_pk_bf16(float lo, float hi) { typedef float f2_t __attribute__((ext_vector_type(2))); typedef __bf16 b2_t __attribute__((ext_vector_type(2))); const f2_t v = {lo, hi}; return __builtin_bit_cast(unsigned, __builtin_convertvector(v, b2_t)); }
;     __device__ __forceinline__ void operator()(const f32x4 (&acc)[2][2][4][2], const Unit& u, int wr, int wc, int fr, int fq) const {
;     ...
;             if (ch > 0) {
;                 const int pc = ch - 1, ai = pc >> 1;
; #pragma unroll
;                 for (int mm = 0; mm < 2; ++mm) { const int m = (pc & 1) * 2 + mm, row = row0 + ai * HALF + m * 16; const size_t off = (size_t)row * ldc + col0;
;                     float s = 0.f;
; #pragma unroll
;                     for (int bj = 0; bj < 2; ++bj)
; #pragma unroll
;                         for (int n = 0; n < 2; ++n) {
;                             const f32x4 o = b[pc & 1][mm][bj][n] + acc[ai][bj][m][n] * scale;
;                             *(f32x4*)(out + off + bj * HALF + n * 16) = o;
;                             if (NORM) { s += (o[0] * o[0] + o[1] * o[1]) + (o[2] * o[2] + o[3] * o[3]);
;                                 u32x2 w; w.x = cvt_pk_bf16(o[0], o[1]); w.y = cvt_pk_bf16(o[2], o[3]); *(u32x2*)(xb + off + bj * HALF + n * 16) = w; }
;                         }
;                     if (NORM) { s += __shfl_xor(s, 16); s += __shfl_xor(s, 32); ssq[(size_t)row * 32 + u.pn * 4 + wc] = s; }
;                 }
	v_pk_add_f32 v[60:61], v[60:61], v[128:129]
	v_pk_add_f32 v[62:63], v[62:63], v[130:131]
	v_pk_add_f32 v[52:53], v[52:53], v[132:133]
	v_pk_add_f32 v[54:55], v[54:55], v[134:135]
	v_pk_add_f32 v[56:57], v[56:57], v[136:137]
	v_pk_add_f32 v[58:59], v[58:59], v[138:139]
	v_pk_add_f32 v[48:49], v[48:49], v[140:141]
	v_pk_add_f32 v[50:51], v[50:51], v[142:143]
	v_pk_add_f32 v[44:45], v[44:45], v[144:145]
	v_pk_add_f32 v[46:47], v[46:47], v[146:147]
	v_pk_add_f32 v[36:37], v[36:37], v[148:149]
	v_pk_add_f32 v[38:39], v[38:39], v[150:151]
	v_pk_add_f32 v[40:41], v[40:41], v[152:153]
	v_pk_add_f32 v[42:43], v[42:43], v[154:155]
	v_pk_add_f32 v[32:33], v[32:33], v[156:157]
	v_pk_add_f32 v[34:35], v[34:35], v[158:159]
	global_store_dwordx4 v216, v[60:63], s[88:89]
	global_store_dwordx4 v216, v[52:55], s[88:89] offset:512
	global_store_dwordx4 v217, v[56:59], s[88:89]
	global_store_dwordx4 v217, v[48:51], s[88:89] offset:512
	global_store_dwordx4 v218, v[44:47], s[88:89]
	global_store_dwordx4 v218, v[36:39], s[88:89] offset:512
	global_store_dwordx4 v219, v[40:43], s[88:89]
	global_store_dwordx4 v219, v[32:35], s[88:89] offset:512
	v_mul_f32_e32 v235, v60, v60
	v_fmac_f32_e32 v235, v61, v61
	v_fmac_f32_e32 v235, v62, v62
	v_fmac_f32_e32 v235, v63, v63
	v_fmac_f32_e32 v235, v52, v52
	v_fmac_f32_e32 v235, v53, v53
	v_fmac_f32_e32 v235, v54, v54
	v_fmac_f32_e32 v235, v55, v55
	v_mul_f32_e32 v236, v56, v56
	v_fmac_f32_e32 v236, v57, v57
	v_fmac_f32_e32 v236, v58, v58
	v_fmac_f32_e32 v236, v59, v59
	v_fmac_f32_e32 v236, v48, v48
	v_fmac_f32_e32 v236, v49, v49
	v_fmac_f32_e32 v236, v50, v50
	v_fmac_f32_e32 v236, v51, v51
	v_mul_f32_e32 v237, v44, v44
	v_fmac_f32_e32 v237, v45, v45
	v_fmac_f32_e32 v237, v46, v46
	v_fmac_f32_e32 v237, v47, v47
	v_fmac_f32_e32 v237, v36, v36
	v_fmac_f32_e32 v237, v37, v37
	v_fmac_f32_e32 v237, v38, v38
	v_fmac_f32_e32 v237, v39, v39
	v_mul_f32_e32 v238, v40, v40
	v_fmac_f32_e32 v238, v41, v41
	v_fmac_f32_e32 v238, v42, v42
	v_fmac_f32_e32 v238, v43, v43
	v_fmac_f32_e32 v238, v32, v32
	v_fmac_f32_e32 v238, v33, v33
	v_fmac_f32_e32 v238, v34, v34
	v_fmac_f32_e32 v238, v35, v35
	v_cvt_pk_bf16_f32 v128, v60, v61
	v_cvt_pk_bf16_f32 v129, v62, v63
	v_cvt_pk_bf16_f32 v132, v52, v53
	v_cvt_pk_bf16_f32 v133, v54, v55
	v_cvt_pk_bf16_f32 v136, v56, v57
	v_cvt_pk_bf16_f32 v137, v58, v59
	v_cvt_pk_bf16_f32 v140, v48, v49
	v_cvt_pk_bf16_f32 v141, v50, v51
	v_cvt_pk_bf16_f32 v144, v44, v45
	v_cvt_pk_bf16_f32 v145, v46, v47
	v_cvt_pk_bf16_f32 v148, v36, v37
	v_cvt_pk_bf16_f32 v149, v38, v39
	v_cvt_pk_bf16_f32 v152, v40, v41
	v_cvt_pk_bf16_f32 v153, v42, v43
	v_cvt_pk_bf16_f32 v156, v32, v33
	v_cvt_pk_bf16_f32 v157, v34, v35
	v_add_u32_e32 v239, 0x80000, v234
	v_add_u32_e32 v190, 0x88000, v234
	v_add_u32_e32 v191, 0x90000, v234
	v_add_u32_e32 v192, 0x98000, v234
	global_store_dwordx2 v239, v[128:129], s[44:45]
	global_store_dwordx2 v239, v[132:133], s[44:45] offset:256
	global_store_dwordx2 v190, v[136:137], s[44:45]
	global_store_dwordx2 v190, v[140:141], s[44:45] offset:256
	global_store_dwordx2 v191, v[144:145], s[44:45]
	global_store_dwordx2 v191, v[148:149], s[44:45] offset:256
	global_store_dwordx2 v192, v[152:153], s[44:45]
	global_store_dwordx2 v192, v[156:157], s[44:45] offset:256
	ds_bpermute_b32 v193, v230, v235
	ds_bpermute_b32 v194, v230, v236
	ds_bpermute_b32 v195, v230, v237
	ds_bpermute_b32 v207, v230, v238
	s_waitcnt lgkmcnt(0)
	v_add_f32_e32 v235, v235, v193
	v_add_f32_e32 v236, v236, v194
	v_add_f32_e32 v237, v237, v195
	v_add_f32_e32 v238, v238, v207
	ds_bpermute_b32 v193, v231, v235
	ds_bpermute_b32 v194, v231, v236
	ds_bpermute_b32 v195, v231, v237
	ds_bpermute_b32 v207, v231, v238
	s_waitcnt lgkmcnt(0)
	v_add_f32_e32 v235, v235, v193
	v_add_f32_e32 v236, v236, v194
	v_add_f32_e32 v237, v237, v195
	v_add_f32_e32 v238, v238, v207
	s_nop 1
	v_add_f32_dpp v193, v235, v235 row_ror:8 row_mask:0xf bank_mask:0xf
	v_add_f32_dpp v194, v236, v236 row_ror:8 row_mask:0xf bank_mask:0xf
	v_add_f32_dpp v195, v237, v237 row_ror:8 row_mask:0xf bank_mask:0xf
	v_add_f32_dpp v207, v238, v238 row_ror:8 row_mask:0xf bank_mask:0xf
	v_cndmask_b32_e64 v248, v193, v194, s[6:7]
	v_add_u32_e32 v250, 0x4000, v232
	v_cndmask_b32_e64 v249, v195, v207, s[6:7]
	v_add_u32_e32 v251, 0x4800, v232
	global_store_dword v250, v248, s[46:47]
	global_store_dword v251, v249, s[46:47]
	s_waitcnt vmcnt(18)
; __device__ __forceinline__ unsigned cvt_pk_bf16(float lo, float hi) { typedef float f2_t __attribute__((ext_vector_type(2))); typedef __bf16 b2_t __attribute__((ext_vector_type(2))); const f2_t v = {lo, hi}; return __builtin_bit_cast(unsigned, __builtin_convertvector(v, b2_t)); }
;     __device__ __forceinline__ void operator()(const f32x4 (&acc)[2][2][4][2], const Unit& u, int wr, int wc, int fr, int fq) const {
;     ...
;             if (ch > 0) {
;                 const int pc = ch - 1, ai = pc >> 1;
; #pragma unroll
;                 for (int mm = 0; mm < 2; ++mm) { const int m = (pc & 1) * 2 + mm, row = row0 + ai * HALF + m * 16; const size_t off = (size_t)row * ldc + col0;
;                     float s = 0.f;
; #pragma unroll
;                     for (int bj = 0; bj < 2; ++bj)
; #pragma unroll
;                         for (int n = 0; n < 2; ++n) {
;                             const f32x4 o = b[pc & 1][mm][bj][n] + acc[ai][bj][m][n] * scale;
;                             *(f32x4*)(out + off + bj * HALF + n * 16) = o;
;                             if (NORM) { s += (o[0] * o[0] + o[1] * o[1]) + (o[2] * o[2] + o[3] * o[3]);
;                                 u32x2 w; w.x = cvt_pk_bf16(o[0], o[1]); w.y = cvt_pk_bf16(o[2], o[3]); *(u32x2*)(xb + off + bj * HALF + n * 16) = w; }
;                         }
;                     if (NORM) { s += __shfl_xor(s, 16); s += __shfl_xor(s, 32); ssq[(size_t)row * 32 + u.pn * 4 + wc] = s; }
;                 }
	v_pk_add_f32 v[28:29], v[28:29], v[164:165]
	v_pk_add_f32 v[30:31], v[30:31], v[166:167]
	v_pk_add_f32 v[20:21], v[20:21], v[168:169]
	v_pk_add_f32 v[22:23], v[22:23], v[170:171]
	v_pk_add_f32 v[24:25], v[24:25], v[172:173]
	v_pk_add_f32 v[26:27], v[26:27], v[174:175]
	v_pk_add_f32 v[16:17], v[16:17], v[176:177]
	v_pk_add_f32 v[18:19], v[18:19], v[178:179]
	v_pk_add_f32 v[12:13], v[12:13], v[180:181]
	v_pk_add_f32 v[14:15], v[14:15], v[182:183]
	v_pk_add_f32 v[4:5], v[4:5], v[184:185]
	v_pk_add_f32 v[6:7], v[6:7], v[186:187]
	v_pk_add_f32 v[8:9], v[8:9], v[208:209]
	v_pk_add_f32 v[10:11], v[10:11], v[210:211]
	v_pk_add_f32 v[0:1], v[0:1], v[212:213]
	v_pk_add_f32 v[2:3], v[2:3], v[214:215]
	global_store_dwordx4 v220, v[28:31], s[88:89]
	global_store_dwordx4 v220, v[20:23], s[88:89] offset:512
	global_store_dwordx4 v221, v[24:27], s[88:89]
	global_store_dwordx4 v221, v[16:19], s[88:89] offset:512
	global_store_dwordx4 v222, v[12:15], s[88:89]
	global_store_dwordx4 v222, v[4:7], s[88:89] offset:512
	global_store_dwordx4 v223, v[8:11], s[88:89]
	global_store_dwordx4 v223, v[0:3], s[88:89] offset:512
	v_mul_f32_e32 v235, v28, v28
	v_fmac_f32_e32 v235, v29, v29
	v_fmac_f32_e32 v235, v30, v30
	v_fmac_f32_e32 v235, v31, v31
	v_fmac_f32_e32 v235, v20, v20
	v_fmac_f32_e32 v235, v21, v21
	v_fmac_f32_e32 v235, v22, v22
	v_fmac_f32_e32 v235, v23, v23
	v_mul_f32_e32 v236, v24, v24
	v_fmac_f32_e32 v236, v25, v25
	v_fmac_f32_e32 v236, v26, v26
	v_fmac_f32_e32 v236, v27, v27
	v_fmac_f32_e32 v236, v16, v16
	v_fmac_f32_e32 v236, v17, v17
	v_fmac_f32_e32 v236, v18, v18
	v_fmac_f32_e32 v236, v19, v19
	v_mul_f32_e32 v237, v12, v12
	v_fmac_f32_e32 v237, v13, v13
	v_fmac_f32_e32 v237, v14, v14
	v_fmac_f32_e32 v237, v15, v15
	v_fmac_f32_e32 v237, v4, v4
	v_fmac_f32_e32 v237, v5, v5
	v_fmac_f32_e32 v237, v6, v6
	v_fmac_f32_e32 v237, v7, v7
	v_mul_f32_e32 v238, v8, v8
	v_fmac_f32_e32 v238, v9, v9
	v_fmac_f32_e32 v238, v10, v10
	v_fmac_f32_e32 v238, v11, v11
	v_fmac_f32_e32 v238, v0, v0
	v_fmac_f32_e32 v238, v1, v1
	v_fmac_f32_e32 v238, v2, v2
	v_fmac_f32_e32 v238, v3, v3
	v_cvt_pk_bf16_f32 v164, v28, v29
	v_cvt_pk_bf16_f32 v165, v30, v31
	v_cvt_pk_bf16_f32 v168, v20, v21
	v_cvt_pk_bf16_f32 v169, v22, v23
	v_cvt_pk_bf16_f32 v172, v24, v25
	v_cvt_pk_bf16_f32 v173, v26, v27
	v_cvt_pk_bf16_f32 v176, v16, v17
	v_cvt_pk_bf16_f32 v177, v18, v19
	v_cvt_pk_bf16_f32 v180, v12, v13
	v_cvt_pk_bf16_f32 v181, v14, v15
	v_cvt_pk_bf16_f32 v184, v4, v5
	v_cvt_pk_bf16_f32 v185, v6, v7
	v_cvt_pk_bf16_f32 v208, v8, v9
	v_cvt_pk_bf16_f32 v209, v10, v11
	v_cvt_pk_bf16_f32 v212, v0, v1
	v_cvt_pk_bf16_f32 v213, v2, v3
	v_add_u32_e32 v239, 0xa0000, v234
	v_add_u32_e32 v190, 0xa8000, v234
	v_add_u32_e32 v191, 0xb0000, v234
	v_add_u32_e32 v192, 0xb8000, v234
	global_store_dwordx2 v239, v[164:165], s[44:45]
	global_store_dwordx2 v239, v[168:169], s[44:45] offset:256
	global_store_dwordx2 v190, v[172:173], s[44:45]
	global_store_dwordx2 v190, v[176:177], s[44:45] offset:256
	global_store_dwordx2 v191, v[180:181], s[44:45]
	global_store_dwordx2 v191, v[184:185], s[44:45] offset:256
	global_store_dwordx2 v192, v[208:209], s[44:45]
	global_store_dwordx2 v192, v[212:213], s[44:45] offset:256
	ds_bpermute_b32 v193, v230, v235
	ds_bpermute_b32 v194, v230, v236
	ds_bpermute_b32 v195, v230, v237
	ds_bpermute_b32 v207, v230, v238
	s_waitcnt lgkmcnt(0)
	v_add_f32_e32 v235, v235, v193
	v_add_f32_e32 v236, v236, v194
	v_add_f32_e32 v237, v237, v195
	v_add_f32_e32 v238, v238, v207
	ds_bpermute_b32 v193, v231, v235
	ds_bpermute_b32 v194, v231, v236
	ds_bpermute_b32 v195, v231, v237
	ds_bpermute_b32 v207, v231, v238
	s_waitcnt lgkmcnt(0)
	v_add_f32_e32 v235, v235, v193
	v_add_f32_e32 v236, v236, v194
	v_add_f32_e32 v237, v237, v195
	v_add_f32_e32 v238, v238, v207
	s_nop 1
	v_add_f32_dpp v193, v235, v235 row_ror:8 row_mask:0xf bank_mask:0xf
	v_add_f32_dpp v194, v236, v236 row_ror:8 row_mask:0xf bank_mask:0xf
	v_add_f32_dpp v195, v237, v237 row_ror:8 row_mask:0xf bank_mask:0xf
	v_add_f32_dpp v207, v238, v238 row_ror:8 row_mask:0xf bank_mask:0xf
	v_cndmask_b32_e64 v248, v193, v194, s[6:7]
	v_add_u32_e32 v250, 0x5000, v232
	v_cndmask_b32_e64 v249, v195, v207, s[6:7]
	v_add_u32_e32 v251, 0x5800, v232
	global_store_dword v250, v248, s[46:47]
	global_store_dword v251, v249, s[46:47]
	s_lshl_b32 s6, s55, 2
	s_ashr_i32 s7, s6, 31
	s_lshl_b64 s[6:7], s[6:7], 2
	s_cbranch_vccnz .LBB0_573
	s_andn2_b64 vcc, exec, s[10:11]
	s_cbranch_vccnz .LBB0_572
	s_barrier
	s_branch .LBB0_572

; __device__ __forceinline__ unsigned xb_add(unsigned* p, unsigned v) { return __hip_atomic_fetch_add(p, v, __ATOMIC_RELAXED, __HIP_MEMORY_SCOPE_AGENT); }
; #define SEAM(k) do { if (IN(k) && IN((k) + 1)) xcd_barrier(bar); } while (0)
; __device__ __forceinline__ void xcd_barrier(const XcdBarrier& b) {
;     asm volatile("s_waitcnt vmcnt(0)" ::: "memory");
;     __syncthreads();
;     if (threadIdx.x == 0) {
;         unsigned* bar = b.bar;
;         __builtin_amdgcn_s_waitcnt(0);
;         unsigned nloc = b.st[0], nx = b.st[1];
;         if (nloc == 0u) { xcd_barrier_complete(bar, b.x, nloc, nx); b.st[0] = nloc; b.st[1] = nx; }
;         const unsigned old = xb_add(&bar[XB_XSUB(b.x)], 1u);
; __global__ void __launch_bounds__(NWAVES * 64, 2) hybrid_fwd(Args args) {
;     ...
;     SEAM(7);
.LBB0_588:
	s_cmp_gt_u32 s75, 8
	s_cselect_b64 s[0:1], -1, 0
	s_and_b64 s[0:1], s[8:9], s[0:1]
	s_andn2_b64 vcc, exec, s[0:1]
	s_cbranch_vccnz .LBB0_638
	s_waitcnt vmcnt(0)
	v_cmp_eq_u32_e32 vcc, 0, v189
	s_waitcnt vmcnt(0) lgkmcnt(0)
	s_barrier
	s_and_saveexec_b64 s[0:1], vcc
	s_cbranch_execz .LBB0_637
	v_mov_b32_e32 v0, 0x20430
	ds_read_b32 v0, v0
	s_waitcnt lgkmcnt(0)
	v_cmp_ne_u32_e32 vcc, 0, v0
	s_cbranch_vccz .Lseam_slow_6
	v_readlane_b32 s8, v255, 0
	v_readlane_b32 s2, v254, 4
	v_readlane_b32 s3, v254, 5
	s_and_b32 s8, s8, 63
	s_lshl_b32 s8, s8, 2
	s_add_i32 s8, s8, 0x100
	v_mov_b32_e32 v0, s8
	v_mov_b32_e32 v1, 1
	s_mov_b32 s9, 0
	s_nop 2
	global_atomic_add v0, v1, s[2:3]
.Lseam_spin_6:
	global_load_dword v2, v0, s[2:3] sc1
	s_add_i32 s9, s9, 1
	s_waitcnt vmcnt(0)
	v_cmp_gt_u32_e32 vcc, 16, v2
	s_cbranch_vccz .Lseam_done_6
	s_cmp_gt_u32 s9, 30000
	s_cbranch_scc1 .Lseam_done_6
	s_sleep 1
	s_branch .Lseam_spin_6

; __device__ __forceinline__ unsigned xb_ld(unsigned* p)              { return __hip_atomic_load(p, __ATOMIC_RELAXED, __HIP_MEMORY_SCOPE_AGENT); }
; __device__ __forceinline__ void xcd_barrier_complete(unsigned* bar, unsigned x, unsigned& nloc, unsigned& nx) {
;     const unsigned G = gridDim.x * gridDim.y * gridDim.z;
;     unsigned sum, cnt, mine, sp = 0u;
;     for (;;) {
;         sum = 0u; cnt = 0u; mine = 0u;
; #pragma unroll
;         for (unsigned j = 0; j < 16; ++j) { const unsigned c = xb_ld(&bar[XB_XCNT(j)]); sum += c; cnt += (c > 0u) ? 1u : 0u; mine = (j == x) ? c : mine; }
; __device__ __forceinline__ void xcd_barrier(const XcdBarrier& b) {
;     ...
;     if (threadIdx.x == 0) {
;         unsigned* bar = b.bar;
;         __builtin_amdgcn_s_waitcnt(0);
;         unsigned nloc = b.st[0], nx = b.st[1];
;         if (nloc == 0u) { xcd_barrier_complete(bar, b.x, nloc, nx); b.st[0] = nloc; b.st[1] = nx; }
.Lseam_slow_6:
	s_add_i32 s2, 0, 0x20420
	v_mov_b32_e32 v0, s2
	s_waitcnt vmcnt(0) expcnt(0) lgkmcnt(0)
	ds_read_b32 v2, v0
	s_add_i32 s2, 0, 0x20424
	v_mov_b32_e32 v0, s2
	ds_read_b32 v0, v0
	s_waitcnt lgkmcnt(1)
	v_cmp_ne_u32_e32 vcc, 0, v2
	s_cbranch_vccnz .LBB0_605
	v_readlane_b32 s4, v254, 2
	v_readlane_b32 s5, v254, 3
	s_load_dwordx2 s[2:3], s[4:5], 0x4
	s_add_u32 s4, s90, 0x2c0200
	s_addc_u32 s5, s91, 0
	s_add_u32 s6, s90, 0x2c0400
	s_addc_u32 s7, s91, 0
	s_add_u32 s8, s90, 0x2c0500
	s_addc_u32 s9, s91, 0
	s_add_u32 s10, s90, 0x2c0600
	s_addc_u32 s11, s91, 0
	s_add_u32 s12, s90, 0x2c0700
	s_addc_u32 s13, s91, 0
	s_add_u32 s14, s90, 0x2c0800
	s_addc_u32 s15, s91, 0
	s_add_u32 s16, s90, 0x2c0900
	s_addc_u32 s17, s91, 0
	s_add_u32 s26, s90, 0x2c0a00
	s_addc_u32 s27, s91, 0
	s_add_u32 s28, s90, 0x2c0b00
	s_addc_u32 s29, s91, 0
	s_add_u32 s30, s90, 0x2c0c00
	s_addc_u32 s31, s91, 0
	s_add_u32 s36, s90, 0x2c0d00
	s_addc_u32 s37, s91, 0
	s_add_u32 s38, s90, 0x2c0e00
	s_addc_u32 s39, s91, 0
	s_add_u32 s42, s90, 0x2c0f00
	s_addc_u32 s43, s91, 0
	s_add_u32 s44, s90, 0x2c1000
	s_addc_u32 s45, s91, 0
	s_add_u32 s46, s90, 0x2c1100
	s_addc_u32 s47, s91, 0
	s_add_u32 s50, s90, 0x2c1200
	s_addc_u32 s51, s91, 0
	s_waitcnt lgkmcnt(0)
	s_mul_i32 s2, s2, s67
	s_add_u32 s52, s90, 0x2c1300
	s_mul_i32 s2, s2, s3
	s_addc_u32 s53, s91, 0
	s_mov_b32 s3, 1
	v_mov_b32_e32 v16, 0
	s_branch .LBB0_593

; #define LAS __attribute__((address_space(3)))
; __device__ __forceinline__ unsigned xb_add(unsigned* p, unsigned v) { return __hip_atomic_fetch_add(p, v, __ATOMIC_RELAXED, __HIP_MEMORY_SCOPE_AGENT); }
; #define SEAM(k) do { if (IN(k) && IN((k) + 1)) xcd_barrier(bar); } while (0)
; __device__ __forceinline__ void xcd_barrier(const XcdBarrier& b) {
;     asm volatile("s_waitcnt vmcnt(0)" ::: "memory");
;     __syncthreads();
;     if (threadIdx.x == 0) {
;         unsigned* bar = b.bar;
;         __builtin_amdgcn_s_waitcnt(0);
;         unsigned nloc = b.st[0], nx = b.st[1];
;         if (nloc == 0u) { xcd_barrier_complete(bar, b.x, nloc, nx); b.st[0] = nloc; b.st[1] = nx; }
;         const unsigned old = xb_add(&bar[XB_XSUB(b.x)], 1u);
; __global__ void __launch_bounds__(NWAVES * 64, 2) hybrid_fwd(Args args) {
;     ...
;     SEAM(7);
;     if (IN(9)) {
;         pg8::Gemm g{Hb, (const bf16*)(ws + WS_WGU2), M, 2 * FF, D}; pg8::StaticOrder S; S.init(M, 2 * FF, G, (int)blockIdx.x);
;         { pg8::Unit u0; if (S.next(0, u0)) panel_scales(lds, ssq, u0.pm, tid); else __syncthreads(); }
;         pg8::EpiSwiGLU<true> E{ACT, FF, (const LAS float*)(lds + RS_OFF)};
;         pg8::gemm_phase<pg8::EpiSwiGLU<true>, pg8::StaticOrder, true, true>(lds, g, S, E);
;     }
;     SEAM(9);
.LBB0_661:
	s_cmp_gt_i32 s75, 10
	s_cselect_b64 s[0:1], -1, 0
	s_and_b64 s[2:3], s[8:9], s[0:1]
	s_andn2_b64 vcc, exec, s[2:3]
	s_cbranch_vccnz .LBB0_711
	s_waitcnt vmcnt(0)
	v_cmp_eq_u32_e32 vcc, 0, v189
	s_waitcnt vmcnt(0) lgkmcnt(0)
	s_barrier
	s_and_saveexec_b64 s[4:5], vcc
	s_cbranch_execz .LBB0_710
	v_mov_b32_e32 v0, 0x20430
	ds_read_b32 v0, v0
	s_waitcnt lgkmcnt(0)
	v_cmp_ne_u32_e32 vcc, 0, v0
	s_cbranch_vccz .Lseam_slow_7
	v_readlane_b32 s8, v255, 0
	v_readlane_b32 s2, v254, 4
	v_readlane_b32 s3, v254, 5
	s_and_b32 s8, s8, 63
	s_lshl_b32 s8, s8, 2
	s_add_i32 s8, s8, 0x100
	v_mov_b32_e32 v0, s8
	v_mov_b32_e32 v1, 1
	s_mov_b32 s9, 0
	s_nop 2
	global_atomic_add v0, v1, s[2:3]
.Lseam_spin_7:
	global_load_dword v2, v0, s[2:3] sc1
	s_add_i32 s9, s9, 1
	s_waitcnt vmcnt(0)
	v_cmp_gt_u32_e32 vcc, 20, v2
	s_cbranch_vccz .Lseam_done_7
	s_cmp_gt_u32 s9, 30000
	s_cbranch_scc1 .Lseam_done_7
	s_sleep 1
	s_branch .Lseam_spin_7

; __device__ __forceinline__ unsigned xb_ld(unsigned* p)              { return __hip_atomic_load(p, __ATOMIC_RELAXED, __HIP_MEMORY_SCOPE_AGENT); }
; __device__ __forceinline__ void xcd_barrier_complete(unsigned* bar, unsigned x, unsigned& nloc, unsigned& nx) {
;     const unsigned G = gridDim.x * gridDim.y * gridDim.z;
;     unsigned sum, cnt, mine, sp = 0u;
;     for (;;) {
;         sum = 0u; cnt = 0u; mine = 0u;
; #pragma unroll
;         for (unsigned j = 0; j < 16; ++j) { const unsigned c = xb_ld(&bar[XB_XCNT(j)]); sum += c; cnt += (c > 0u) ? 1u : 0u; mine = (j == x) ? c : mine; }
; __device__ __forceinline__ void xcd_barrier(const XcdBarrier& b) {
;     ...
;     if (threadIdx.x == 0) {
;         unsigned* bar = b.bar;
;         __builtin_amdgcn_s_waitcnt(0);
;         unsigned nloc = b.st[0], nx = b.st[1];
;         if (nloc == 0u) { xcd_barrier_complete(bar, b.x, nloc, nx); b.st[0] = nloc; b.st[1] = nx; }
.Lseam_slow_7:
	s_add_i32 s2, 0, 0x20420
	v_mov_b32_e32 v0, s2
	s_waitcnt vmcnt(0) expcnt(0) lgkmcnt(0)
	ds_read_b32 v2, v0
	s_add_i32 s2, 0, 0x20424
	v_mov_b32_e32 v0, s2
	ds_read_b32 v0, v0
	s_waitcnt lgkmcnt(1)
	v_cmp_ne_u32_e32 vcc, 0, v2
	s_cbranch_vccnz .LBB0_678
	v_readlane_b32 s6, v254, 2
	v_readlane_b32 s7, v254, 3
	s_load_dwordx2 s[2:3], s[6:7], 0x4
	s_add_u32 s6, s90, 0x2c0200
	s_addc_u32 s7, s91, 0
	s_add_u32 s8, s90, 0x2c0400
	s_addc_u32 s9, s91, 0
	s_add_u32 s10, s90, 0x2c0500
	s_addc_u32 s11, s91, 0
	s_add_u32 s12, s90, 0x2c0600
	s_addc_u32 s13, s91, 0
	s_add_u32 s14, s90, 0x2c0700
	s_addc_u32 s15, s91, 0
	s_add_u32 s16, s90, 0x2c0800
	s_addc_u32 s17, s91, 0
	s_add_u32 s24, s90, 0x2c0900
	s_addc_u32 s25, s91, 0
	s_add_u32 s26, s90, 0x2c0a00
	s_addc_u32 s27, s91, 0
	s_add_u32 s28, s90, 0x2c0b00
	s_addc_u32 s29, s91, 0
	s_add_u32 s30, s90, 0x2c0c00
	s_addc_u32 s31, s91, 0
	s_add_u32 s36, s90, 0x2c0d00
	s_addc_u32 s37, s91, 0
	s_add_u32 s38, s90, 0x2c0e00
	s_addc_u32 s39, s91, 0
	s_add_u32 s42, s90, 0x2c0f00
	s_addc_u32 s43, s91, 0
	s_add_u32 s44, s90, 0x2c1000
	s_addc_u32 s45, s91, 0
	s_add_u32 s46, s90, 0x2c1100
	s_addc_u32 s47, s91, 0
	s_add_u32 s50, s90, 0x2c1200
	s_addc_u32 s51, s91, 0
	s_waitcnt lgkmcnt(0)
	s_mul_i32 s2, s2, s67
	s_add_u32 s52, s90, 0x2c1300
	s_mul_i32 s2, s2, s3
	s_addc_u32 s53, s91, 0
	s_mov_b32 s3, 1
	v_mov_b32_e32 v16, 0
	s_branch .LBB0_666

;     __device__ __forceinline__ void operator()(const f32x4 (&acc)[2][2][4][2], const Unit& u, int wr, int wc, int fr, int fq) const {
;         int row0 = u.pm * BM + wr * 64 + fr, col0 = u.pn * BM + wc * 32 + 4 * fq;
;         asm volatile("" : "+v"(row0), "+v"(col0));
;         f32x4 b[2][2][2][2];
; #pragma unroll
;         for (int ch = 0; ch <= 4; ++ch) {
;             if (ch < 4) {
; #pragma unroll
;                 for (int mm = 0; mm < 2; ++mm) { const size_t off = (size_t)(row0 + (ch >> 1) * HALF + ((ch & 1) * 2 + mm) * 16) * ldc + col0;
; #pragma unroll
;                     for (int bj = 0; bj < 2; ++bj)
; #pragma unroll
;                         for (int n = 0; n < 2; ++n) b[ch & 1][mm][bj][n] = *(const f32x4*)(base + off + bj * HALF + n * 16); }
.LBB0_736:
	s_and_b64 vcc, exec, s[0:1]
	s_mov_b64 s[0:1], -1
	v_bfe_u32 v225, v140, 3, 1
	v_and_b32_e32 v226, 0x77, v140
	v_lshl_add_u32 v227, v225, 4, v141
	v_lshl_add_u32 v223, s49, 8, v226
	v_lshl_or_b32 v224, s50, 8, v227
	v_lshlrev_b32_e32 v222, 13, v223
	v_lshl_add_u32 v222, v224, 2, v222
	s_nop 7
	v_mov_b32_e32 v244, v104
	v_mov_b32_e32 v245, v105
	v_mov_b32_e32 v246, v106
	v_mov_b32_e32 v247, v107
	v_mov_b32_dpp v104, v108 row_ror:8 row_mask:0xf bank_mask:0x3
	v_mov_b32_dpp v105, v109 row_ror:8 row_mask:0xf bank_mask:0x3
	v_mov_b32_dpp v106, v110 row_ror:8 row_mask:0xf bank_mask:0x3
	v_mov_b32_dpp v107, v111 row_ror:8 row_mask:0xf bank_mask:0x3
	v_mov_b32_dpp v108, v244 row_ror:8 row_mask:0xf bank_mask:0xc
	v_mov_b32_dpp v109, v245 row_ror:8 row_mask:0xf bank_mask:0xc
	v_mov_b32_dpp v110, v246 row_ror:8 row_mask:0xf bank_mask:0xc
	v_mov_b32_dpp v111, v247 row_ror:8 row_mask:0xf bank_mask:0xc
	v_mov_b32_e32 v244, v120
	v_mov_b32_e32 v245, v121
	v_mov_b32_e32 v246, v122
	v_mov_b32_e32 v247, v123
	v_mov_b32_dpp v120, v124 row_ror:8 row_mask:0xf bank_mask:0x3
	v_mov_b32_dpp v121, v125 row_ror:8 row_mask:0xf bank_mask:0x3
	v_mov_b32_dpp v122, v126 row_ror:8 row_mask:0xf bank_mask:0x3
	v_mov_b32_dpp v123, v127 row_ror:8 row_mask:0xf bank_mask:0x3
	v_mov_b32_dpp v124, v244 row_ror:8 row_mask:0xf bank_mask:0xc
	v_mov_b32_dpp v125, v245 row_ror:8 row_mask:0xf bank_mask:0xc
	v_mov_b32_dpp v126, v246 row_ror:8 row_mask:0xf bank_mask:0xc
	v_mov_b32_dpp v127, v247 row_ror:8 row_mask:0xf bank_mask:0xc
	v_mov_b32_e32 v244, v96
	v_mov_b32_e32 v245, v97
	v_mov_b32_e32 v246, v98
	v_mov_b32_e32 v247, v99
	v_mov_b32_dpp v96, v100 row_ror:8 row_mask:0xf bank_mask:0x3
	v_mov_b32_dpp v97, v101 row_ror:8 row_mask:0xf bank_mask:0x3
	v_mov_b32_dpp v98, v102 row_ror:8 row_mask:0xf bank_mask:0x3
	v_mov_b32_dpp v99, v103 row_ror:8 row_mask:0xf bank_mask:0x3
	v_mov_b32_dpp v100, v244 row_ror:8 row_mask:0xf bank_mask:0xc
	v_mov_b32_dpp v101, v245 row_ror:8 row_mask:0xf bank_mask:0xc
	v_mov_b32_dpp v102, v246 row_ror:8 row_mask:0xf bank_mask:0xc
	v_mov_b32_dpp v103, v247 row_ror:8 row_mask:0xf bank_mask:0xc
	v_mov_b32_e32 v244, v112
	v_mov_b32_e32 v245, v113
	v_mov_b32_e32 v246, v114
	v_mov_b32_e32 v247, v115
	v_mov_b32_dpp v112, v116 row_ror:8 row_mask:0xf bank_mask:0x3
	v_mov_b32_dpp v113, v117 row_ror:8 row_mask:0xf bank_mask:0x3
	v_mov_b32_dpp v114, v118 row_ror:8 row_mask:0xf bank_mask:0x3
	v_mov_b32_dpp v115, v119 row_ror:8 row_mask:0xf bank_mask:0x3
	v_mov_b32_dpp v116, v244 row_ror:8 row_mask:0xf bank_mask:0xc
	v_mov_b32_dpp v117, v245 row_ror:8 row_mask:0xf bank_mask:0xc
	v_mov_b32_dpp v118, v246 row_ror:8 row_mask:0xf bank_mask:0xc
	v_mov_b32_dpp v119, v247 row_ror:8 row_mask:0xf bank_mask:0xc
	v_mov_b32_e32 v244, v84
	v_mov_b32_e32 v245, v85
	v_mov_b32_e32 v246, v86
	v_mov_b32_e32 v247, v87
	v_mov_b32_dpp v84, v92 row_ror:8 row_mask:0xf bank_mask:0x3
	v_mov_b32_dpp v85, v93 row_ror:8 row_mask:0xf bank_mask:0x3
	v_mov_b32_dpp v86, v94 row_ror:8 row_mask:0xf bank_mask:0x3
	v_mov_b32_dpp v87, v95 row_ror:8 row_mask:0xf bank_mask:0x3
	v_mov_b32_dpp v92, v244 row_ror:8 row_mask:0xf bank_mask:0xc
	v_mov_b32_dpp v93, v245 row_ror:8 row_mask:0xf bank_mask:0xc
	v_mov_b32_dpp v94, v246 row_ror:8 row_mask:0xf bank_mask:0xc
	v_mov_b32_dpp v95, v247 row_ror:8 row_mask:0xf bank_mask:0xc
	v_mov_b32_e32 v244, v80
	v_mov_b32_e32 v245, v81
	v_mov_b32_e32 v246, v82
	v_mov_b32_e32 v247, v83
	v_mov_b32_dpp v80, v88 row_ror:8 row_mask:0xf bank_mask:0x3
	v_mov_b32_dpp v81, v89 row_ror:8 row_mask:0xf bank_mask:0x3
	v_mov_b32_dpp v82, v90 row_ror:8 row_mask:0xf bank_mask:0x3
	v_mov_b32_dpp v83, v91 row_ror:8 row_mask:0xf bank_mask:0x3
	v_mov_b32_dpp v88, v244 row_ror:8 row_mask:0xf bank_mask:0xc
	v_mov_b32_dpp v89, v245 row_ror:8 row_mask:0xf bank_mask:0xc
	v_mov_b32_dpp v90, v246 row_ror:8 row_mask:0xf bank_mask:0xc
	v_mov_b32_dpp v91, v247 row_ror:8 row_mask:0xf bank_mask:0xc
	v_mov_b32_e32 v244, v68
	v_mov_b32_e32 v245, v69
	v_mov_b32_e32 v246, v70
	v_mov_b32_e32 v247, v71
	v_mov_b32_dpp v68, v76 row_ror:8 row_mask:0xf bank_mask:0x3
	v_mov_b32_dpp v69, v77 row_ror:8 row_mask:0xf bank_mask:0x3
	v_mov_b32_dpp v70, v78 row_ror:8 row_mask:0xf bank_mask:0x3
	v_mov_b32_dpp v71, v79 row_ror:8 row_mask:0xf bank_mask:0x3
	v_mov_b32_dpp v76, v244 row_ror:8 row_mask:0xf bank_mask:0xc
	v_mov_b32_dpp v77, v245 row_ror:8 row_mask:0xf bank_mask:0xc
	v_mov_b32_dpp v78, v246 row_ror:8 row_mask:0xf bank_mask:0xc
	v_mov_b32_dpp v79, v247 row_ror:8 row_mask:0xf bank_mask:0xc
	v_mov_b32_e32 v244, v64
	v_mov_b32_e32 v245, v65
	v_mov_b32_e32 v246, v66
	v_mov_b32_e32 v247, v67
	v_mov_b32_dpp v64, v72 row_ror:8 row_mask:0xf bank_mask:0x3
	v_mov_b32_dpp v65, v73 row_ror:8 row_mask:0xf bank_mask:0x3
	v_mov_b32_dpp v66, v74 row_ror:8 row_mask:0xf bank_mask:0x3
	v_mov_b32_dpp v67, v75 row_ror:8 row_mask:0xf bank_mask:0x3
	v_mov_b32_dpp v72, v244 row_ror:8 row_mask:0xf bank_mask:0xc
	v_mov_b32_dpp v73, v245 row_ror:8 row_mask:0xf bank_mask:0xc
	v_mov_b32_dpp v74, v246 row_ror:8 row_mask:0xf bank_mask:0xc
	v_mov_b32_dpp v75, v247 row_ror:8 row_mask:0xf bank_mask:0xc
	v_mov_b32_e32 v244, v40
	v_mov_b32_e32 v245, v41
	v_mov_b32_e32 v246, v42
	v_mov_b32_e32 v247, v43
	v_mov_b32_dpp v40, v44 row_ror:8 row_mask:0xf bank_mask:0x3
	v_mov_b32_dpp v41, v45 row_ror:8 row_mask:0xf bank_mask:0x3
	v_mov_b32_dpp v42, v46 row_ror:8 row_mask:0xf bank_mask:0x3
	v_mov_b32_dpp v43, v47 row_ror:8 row_mask:0xf bank_mask:0x3
	v_mov_b32_dpp v44, v244 row_ror:8 row_mask:0xf bank_mask:0xc
	v_mov_b32_dpp v45, v245 row_ror:8 row_mask:0xf bank_mask:0xc
	v_mov_b32_dpp v46, v246 row_ror:8 row_mask:0xf bank_mask:0xc
;     __device__ __forceinline__ void operator()(const f32x4 (&acc)[2][2][4][2], const Unit& u, int wr, int wc, int fr, int fq) const {
;     ...
;         for (int ch = 0; ch <= 4; ++ch) {
;             if (ch < 4) {
; #pragma unroll
;                 for (int mm = 0; mm < 2; ++mm) { const size_t off = (size_t)(row0 + (ch >> 1) * HALF + ((ch & 1) * 2 + mm) * 16) * ldc + col0;
; #pragma unroll
;                     for (int bj = 0; bj < 2; ++bj)
; #pragma unroll
;                         for (int n = 0; n < 2; ++n) b[ch & 1][mm][bj][n] = *(const f32x4*)(base + off + bj * HALF + n * 16); }
	v_mov_b32_dpp v47, v247 row_ror:8 row_mask:0xf bank_mask:0xc
	v_mov_b32_e32 v244, v56
	v_mov_b32_e32 v245, v57
	v_mov_b32_e32 v246, v58
	v_mov_b32_e32 v247, v59
	v_mov_b32_dpp v56, v60 row_ror:8 row_mask:0xf bank_mask:0x3
	v_mov_b32_dpp v57, v61 row_ror:8 row_mask:0xf bank_mask:0x3
	v_mov_b32_dpp v58, v62 row_ror:8 row_mask:0xf bank_mask:0x3
	v_mov_b32_dpp v59, v63 row_ror:8 row_mask:0xf bank_mask:0x3
	v_mov_b32_dpp v60, v244 row_ror:8 row_mask:0xf bank_mask:0xc
	v_mov_b32_dpp v61, v245 row_ror:8 row_mask:0xf bank_mask:0xc
	v_mov_b32_dpp v62, v246 row_ror:8 row_mask:0xf bank_mask:0xc
	v_mov_b32_dpp v63, v247 row_ror:8 row_mask:0xf bank_mask:0xc
	v_mov_b32_e32 v244, v32
	v_mov_b32_e32 v245, v33
	v_mov_b32_e32 v246, v34
	v_mov_b32_e32 v247, v35
	v_mov_b32_dpp v32, v36 row_ror:8 row_mask:0xf bank_mask:0x3
	v_mov_b32_dpp v33, v37 row_ror:8 row_mask:0xf bank_mask:0x3
	v_mov_b32_dpp v34, v38 row_ror:8 row_mask:0xf bank_mask:0x3
	v_mov_b32_dpp v35, v39 row_ror:8 row_mask:0xf bank_mask:0x3
	v_mov_b32_dpp v36, v244 row_ror:8 row_mask:0xf bank_mask:0xc
	v_mov_b32_dpp v37, v245 row_ror:8 row_mask:0xf bank_mask:0xc
	v_mov_b32_dpp v38, v246 row_ror:8 row_mask:0xf bank_mask:0xc
	v_mov_b32_dpp v39, v247 row_ror:8 row_mask:0xf bank_mask:0xc
	v_mov_b32_e32 v244, v48
	v_mov_b32_e32 v245, v49
	v_mov_b32_e32 v246, v50
	v_mov_b32_e32 v247, v51
	v_mov_b32_dpp v48, v52 row_ror:8 row_mask:0xf bank_mask:0x3
	v_mov_b32_dpp v49, v53 row_ror:8 row_mask:0xf bank_mask:0x3
	v_mov_b32_dpp v50, v54 row_ror:8 row_mask:0xf bank_mask:0x3
	v_mov_b32_dpp v51, v55 row_ror:8 row_mask:0xf bank_mask:0x3
	v_mov_b32_dpp v52, v244 row_ror:8 row_mask:0xf bank_mask:0xc
	v_mov_b32_dpp v53, v245 row_ror:8 row_mask:0xf bank_mask:0xc
	v_mov_b32_dpp v54, v246 row_ror:8 row_mask:0xf bank_mask:0xc
	v_mov_b32_dpp v55, v247 row_ror:8 row_mask:0xf bank_mask:0xc
	v_mov_b32_e32 v244, v20
	v_mov_b32_e32 v245, v21
	v_mov_b32_e32 v246, v22
	v_mov_b32_e32 v247, v23
	v_mov_b32_dpp v20, v28 row_ror:8 row_mask:0xf bank_mask:0x3
	v_mov_b32_dpp v21, v29 row_ror:8 row_mask:0xf bank_mask:0x3
	v_mov_b32_dpp v22, v30 row_ror:8 row_mask:0xf bank_mask:0x3
	v_mov_b32_dpp v23, v31 row_ror:8 row_mask:0xf bank_mask:0x3
	v_mov_b32_dpp v28, v244 row_ror:8 row_mask:0xf bank_mask:0xc
	v_mov_b32_dpp v29, v245 row_ror:8 row_mask:0xf bank_mask:0xc
	v_mov_b32_dpp v30, v246 row_ror:8 row_mask:0xf bank_mask:0xc
	v_mov_b32_dpp v31, v247 row_ror:8 row_mask:0xf bank_mask:0xc
	v_mov_b32_e32 v244, v16
	v_mov_b32_e32 v245, v17
	v_mov_b32_e32 v246, v18
	v_mov_b32_e32 v247, v19
	v_mov_b32_dpp v16, v24 row_ror:8 row_mask:0xf bank_mask:0x3
	v_mov_b32_dpp v17, v25 row_ror:8 row_mask:0xf bank_mask:0x3
	v_mov_b32_dpp v18, v26 row_ror:8 row_mask:0xf bank_mask:0x3
	v_mov_b32_dpp v19, v27 row_ror:8 row_mask:0xf bank_mask:0x3
	v_mov_b32_dpp v24, v244 row_ror:8 row_mask:0xf bank_mask:0xc
	v_mov_b32_dpp v25, v245 row_ror:8 row_mask:0xf bank_mask:0xc
	v_mov_b32_dpp v26, v246 row_ror:8 row_mask:0xf bank_mask:0xc
	v_mov_b32_dpp v27, v247 row_ror:8 row_mask:0xf bank_mask:0xc
	v_mov_b32_e32 v244, v4
	v_mov_b32_e32 v245, v5
	v_mov_b32_e32 v246, v6
	v_mov_b32_e32 v247, v7
	v_mov_b32_dpp v4, v12 row_ror:8 row_mask:0xf bank_mask:0x3
	v_mov_b32_dpp v5, v13 row_ror:8 row_mask:0xf bank_mask:0x3
	v_mov_b32_dpp v6, v14 row_ror:8 row_mask:0xf bank_mask:0x3
	v_mov_b32_dpp v7, v15 row_ror:8 row_mask:0xf bank_mask:0x3
	v_mov_b32_dpp v12, v244 row_ror:8 row_mask:0xf bank_mask:0xc
	v_mov_b32_dpp v13, v245 row_ror:8 row_mask:0xf bank_mask:0xc
	v_mov_b32_dpp v14, v246 row_ror:8 row_mask:0xf bank_mask:0xc
	v_mov_b32_dpp v15, v247 row_ror:8 row_mask:0xf bank_mask:0xc
	v_mov_b32_e32 v244, v0
	v_mov_b32_e32 v245, v1
	v_mov_b32_e32 v246, v2
	v_mov_b32_e32 v247, v3
	v_mov_b32_dpp v0, v8 row_ror:8 row_mask:0xf bank_mask:0x3
	v_mov_b32_dpp v1, v9 row_ror:8 row_mask:0xf bank_mask:0x3
	v_mov_b32_dpp v2, v10 row_ror:8 row_mask:0xf bank_mask:0x3
	v_mov_b32_dpp v3, v11 row_ror:8 row_mask:0xf bank_mask:0x3
	v_mov_b32_dpp v8, v244 row_ror:8 row_mask:0xf bank_mask:0xc
	v_mov_b32_dpp v9, v245 row_ror:8 row_mask:0xf bank_mask:0xc
	v_mov_b32_dpp v10, v246 row_ror:8 row_mask:0xf bank_mask:0xc
	v_mov_b32_dpp v11, v247 row_ror:8 row_mask:0xf bank_mask:0xc
	v_add_u32_e32 v214, 0x0, v222
	v_add_u32_e32 v215, 0x10000, v222
	v_add_u32_e32 v216, 0x20000, v222
	v_add_u32_e32 v217, 0x30000, v222
	global_load_dwordx4 v[148:151], v214, s[88:89]
	global_load_dwordx4 v[152:155], v214, s[88:89] offset:512
	global_load_dwordx4 v[156:159], v215, s[88:89]
	global_load_dwordx4 v[160:163], v215, s[88:89] offset:512
	global_load_dwordx4 v[164:167], v216, s[88:89]
	global_load_dwordx4 v[168:171], v216, s[88:89] offset:512
	global_load_dwordx4 v[172:175], v217, s[88:89]
	global_load_dwordx4 v[176:179], v217, s[88:89] offset:512
	v_add_u32_e32 v218, 0x40000, v222
	v_add_u32_e32 v219, 0x50000, v222
	v_add_u32_e32 v220, 0x60000, v222
	v_add_u32_e32 v221, 0x70000, v222
	global_load_dwordx4 v[180:183], v218, s[88:89]
	global_load_dwordx4 v[184:187], v218, s[88:89] offset:512
	global_load_dwordx4 v[190:193], v219, s[88:89]
	global_load_dwordx4 v[194:197], v219, s[88:89] offset:512
	global_load_dwordx4 v[198:201], v220, s[88:89]
	global_load_dwordx4 v[202:205], v220, s[88:89] offset:512
	global_load_dwordx4 v[206:209], v221, s[88:89]
	global_load_dwordx4 v[210:213], v221, s[88:89] offset:512
	s_waitcnt vmcnt(8)
;     __device__ __forceinline__ void operator()(const f32x4 (&acc)[2][2][4][2], const Unit& u, int wr, int wc, int fr, int fq) const {
;     ...
;             if (ch > 0) {
;                 const int pc = ch - 1, ai = pc >> 1;
; #pragma unroll
;                 for (int mm = 0; mm < 2; ++mm) { const int m = (pc & 1) * 2 + mm, row = row0 + ai * HALF + m * 16; const size_t off = (size_t)row * ldc + col0;
;                     float s = 0.f;
; #pragma unroll
;                     for (int bj = 0; bj < 2; ++bj)
; #pragma unroll
;                         for (int n = 0; n < 2; ++n) {
;                             const f32x4 o = b[pc & 1][mm][bj][n] + acc[ai][bj][m][n] * scale;
;                             *(f32x4*)(out + off + bj * HALF + n * 16) = o;
	v_pk_fma_f32 v[108:109], v[108:109], 0.5, v[148:149] op_sel_hi:[1,0,1]
	v_pk_fma_f32 v[110:111], v[110:111], 0.5, v[150:151] op_sel_hi:[1,0,1]
	v_pk_fma_f32 v[124:125], v[124:125], 0.5, v[152:153] op_sel_hi:[1,0,1]
	v_pk_fma_f32 v[126:127], v[126:127], 0.5, v[154:155] op_sel_hi:[1,0,1]
	v_pk_fma_f32 v[104:105], v[104:105], 0.5, v[156:157] op_sel_hi:[1,0,1]
	v_pk_fma_f32 v[106:107], v[106:107], 0.5, v[158:159] op_sel_hi:[1,0,1]
	v_pk_fma_f32 v[120:121], v[120:121], 0.5, v[160:161] op_sel_hi:[1,0,1]
	v_pk_fma_f32 v[122:123], v[122:123], 0.5, v[162:163] op_sel_hi:[1,0,1]
	v_pk_fma_f32 v[100:101], v[100:101], 0.5, v[164:165] op_sel_hi:[1,0,1]
	v_pk_fma_f32 v[102:103], v[102:103], 0.5, v[166:167] op_sel_hi:[1,0,1]
	v_pk_fma_f32 v[116:117], v[116:117], 0.5, v[168:169] op_sel_hi:[1,0,1]
	v_pk_fma_f32 v[118:119], v[118:119], 0.5, v[170:171] op_sel_hi:[1,0,1]
	v_pk_fma_f32 v[96:97], v[96:97], 0.5, v[172:173] op_sel_hi:[1,0,1]
	v_pk_fma_f32 v[98:99], v[98:99], 0.5, v[174:175] op_sel_hi:[1,0,1]
	v_pk_fma_f32 v[112:113], v[112:113], 0.5, v[176:177] op_sel_hi:[1,0,1]
	v_pk_fma_f32 v[114:115], v[114:115], 0.5, v[178:179] op_sel_hi:[1,0,1]
	global_store_dwordx4 v214, v[108:111], s[88:89]
	global_store_dwordx4 v214, v[124:127], s[88:89] offset:512
	global_store_dwordx4 v215, v[104:107], s[88:89]
	global_store_dwordx4 v215, v[120:123], s[88:89] offset:512
	global_store_dwordx4 v216, v[100:103], s[88:89]
	global_store_dwordx4 v216, v[116:119], s[88:89] offset:512
	global_store_dwordx4 v217, v[96:99], s[88:89]
	global_store_dwordx4 v217, v[112:115], s[88:89] offset:512
	v_add_u32_e32 v214, 0x100000, v222
	v_add_u32_e32 v215, 0x110000, v222
	v_add_u32_e32 v216, 0x120000, v222
	v_add_u32_e32 v217, 0x130000, v222
	global_load_dwordx4 v[148:151], v214, s[88:89]
	global_load_dwordx4 v[152:155], v214, s[88:89] offset:512
	global_load_dwordx4 v[156:159], v215, s[88:89]
	global_load_dwordx4 v[160:163], v215, s[88:89] offset:512
	global_load_dwordx4 v[164:167], v216, s[88:89]
	global_load_dwordx4 v[168:171], v216, s[88:89] offset:512
	global_load_dwordx4 v[172:175], v217, s[88:89]
	global_load_dwordx4 v[176:179], v217, s[88:89] offset:512
	s_waitcnt vmcnt(16)
	v_pk_fma_f32 v[92:93], v[92:93], 0.5, v[180:181] op_sel_hi:[1,0,1]
	v_pk_fma_f32 v[94:95], v[94:95], 0.5, v[182:183] op_sel_hi:[1,0,1]
	v_pk_fma_f32 v[88:89], v[88:89], 0.5, v[184:185] op_sel_hi:[1,0,1]
	v_pk_fma_f32 v[90:91], v[90:91], 0.5, v[186:187] op_sel_hi:[1,0,1]
	v_pk_fma_f32 v[84:85], v[84:85], 0.5, v[190:191] op_sel_hi:[1,0,1]
	v_pk_fma_f32 v[86:87], v[86:87], 0.5, v[192:193] op_sel_hi:[1,0,1]
	v_pk_fma_f32 v[80:81], v[80:81], 0.5, v[194:195] op_sel_hi:[1,0,1]
	v_pk_fma_f32 v[82:83], v[82:83], 0.5, v[196:197] op_sel_hi:[1,0,1]
	v_pk_fma_f32 v[76:77], v[76:77], 0.5, v[198:199] op_sel_hi:[1,0,1]
	v_pk_fma_f32 v[78:79], v[78:79], 0.5, v[200:201] op_sel_hi:[1,0,1]
	v_pk_fma_f32 v[72:73], v[72:73], 0.5, v[202:203] op_sel_hi:[1,0,1]
	v_pk_fma_f32 v[74:75], v[74:75], 0.5, v[204:205] op_sel_hi:[1,0,1]
	v_pk_fma_f32 v[68:69], v[68:69], 0.5, v[206:207] op_sel_hi:[1,0,1]
	v_pk_fma_f32 v[70:71], v[70:71], 0.5, v[208:209] op_sel_hi:[1,0,1]
	v_pk_fma_f32 v[64:65], v[64:65], 0.5, v[210:211] op_sel_hi:[1,0,1]
	v_pk_fma_f32 v[66:67], v[66:67], 0.5, v[212:213] op_sel_hi:[1,0,1]
	global_store_dwordx4 v218, v[92:95], s[88:89]
	global_store_dwordx4 v218, v[88:91], s[88:89] offset:512
	global_store_dwordx4 v219, v[84:87], s[88:89]
	global_store_dwordx4 v219, v[80:83], s[88:89] offset:512
	global_store_dwordx4 v220, v[76:79], s[88:89]
	global_store_dwordx4 v220, v[72:75], s[88:89] offset:512
	global_store_dwordx4 v221, v[68:71], s[88:89]
	global_store_dwordx4 v221, v[64:67], s[88:89] offset:512
	v_add_u32_e32 v218, 0x140000, v222
	v_add_u32_e32 v219, 0x150000, v222
	v_add_u32_e32 v220, 0x160000, v222
	v_add_u32_e32 v221, 0x170000, v222
	global_load_dwordx4 v[180:183], v218, s[88:89]
	global_load_dwordx4 v[184:187], v218, s[88:89] offset:512
	global_load_dwordx4 v[190:193], v219, s[88:89]
	global_load_dwordx4 v[194:197], v219, s[88:89] offset:512
	global_load_dwordx4 v[198:201], v220, s[88:89]
	global_load_dwordx4 v[202:205], v220, s[88:89] offset:512
	global_load_dwordx4 v[206:209], v221, s[88:89]
	global_load_dwordx4 v[210:213], v221, s[88:89] offset:512
	s_waitcnt vmcnt(16)
;     __device__ __forceinline__ void operator()(const f32x4 (&acc)[2][2][4][2], const Unit& u, int wr, int wc, int fr, int fq) const {
;     ...
;             if (ch > 0) {
;                 const int pc = ch - 1, ai = pc >> 1;
; #pragma unroll
;                 for (int mm = 0; mm < 2; ++mm) { const int m = (pc & 1) * 2 + mm, row = row0 + ai * HALF + m * 16; const size_t off = (size_t)row * ldc + col0;
;                     float s = 0.f;
; #pragma unroll
;                     for (int bj = 0; bj < 2; ++bj)
; #pragma unroll
;                         for (int n = 0; n < 2; ++n) {
;                             const f32x4 o = b[pc & 1][mm][bj][n] + acc[ai][bj][m][n] * scale;
;                             *(f32x4*)(out + off + bj * HALF + n * 16) = o;
	v_pk_fma_f32 v[44:45], v[44:45], 0.5, v[148:149] op_sel_hi:[1,0,1]
	v_pk_fma_f32 v[46:47], v[46:47], 0.5, v[150:151] op_sel_hi:[1,0,1]
	v_pk_fma_f32 v[60:61], v[60:61], 0.5, v[152:153] op_sel_hi:[1,0,1]
	v_pk_fma_f32 v[62:63], v[62:63], 0.5, v[154:155] op_sel_hi:[1,0,1]
	v_pk_fma_f32 v[40:41], v[40:41], 0.5, v[156:157] op_sel_hi:[1,0,1]
	v_pk_fma_f32 v[42:43], v[42:43], 0.5, v[158:159] op_sel_hi:[1,0,1]
	v_pk_fma_f32 v[56:57], v[56:57], 0.5, v[160:161] op_sel_hi:[1,0,1]
	v_pk_fma_f32 v[58:59], v[58:59], 0.5, v[162:163] op_sel_hi:[1,0,1]
	v_pk_fma_f32 v[36:37], v[36:37], 0.5, v[164:165] op_sel_hi:[1,0,1]
	v_pk_fma_f32 v[38:39], v[38:39], 0.5, v[166:167] op_sel_hi:[1,0,1]
	v_pk_fma_f32 v[52:53], v[52:53], 0.5, v[168:169] op_sel_hi:[1,0,1]
	v_pk_fma_f32 v[54:55], v[54:55], 0.5, v[170:171] op_sel_hi:[1,0,1]
	v_pk_fma_f32 v[32:33], v[32:33], 0.5, v[172:173] op_sel_hi:[1,0,1]
	v_pk_fma_f32 v[34:35], v[34:35], 0.5, v[174:175] op_sel_hi:[1,0,1]
	v_pk_fma_f32 v[48:49], v[48:49], 0.5, v[176:177] op_sel_hi:[1,0,1]
	v_pk_fma_f32 v[50:51], v[50:51], 0.5, v[178:179] op_sel_hi:[1,0,1]
	global_store_dwordx4 v214, v[44:47], s[88:89]
	global_store_dwordx4 v214, v[60:63], s[88:89] offset:512
	global_store_dwordx4 v215, v[40:43], s[88:89]
	global_store_dwordx4 v215, v[56:59], s[88:89] offset:512
	global_store_dwordx4 v216, v[36:39], s[88:89]
	global_store_dwordx4 v216, v[52:55], s[88:89] offset:512
	global_store_dwordx4 v217, v[32:35], s[88:89]
	global_store_dwordx4 v217, v[48:51], s[88:89] offset:512
	s_waitcnt vmcnt(8)
	v_pk_fma_f32 v[28:29], v[28:29], 0.5, v[180:181] op_sel_hi:[1,0,1]
	v_pk_fma_f32 v[30:31], v[30:31], 0.5, v[182:183] op_sel_hi:[1,0,1]
	v_pk_fma_f32 v[24:25], v[24:25], 0.5, v[184:185] op_sel_hi:[1,0,1]
	v_pk_fma_f32 v[26:27], v[26:27], 0.5, v[186:187] op_sel_hi:[1,0,1]
	v_pk_fma_f32 v[20:21], v[20:21], 0.5, v[190:191] op_sel_hi:[1,0,1]
	v_pk_fma_f32 v[22:23], v[22:23], 0.5, v[192:193] op_sel_hi:[1,0,1]
	v_pk_fma_f32 v[16:17], v[16:17], 0.5, v[194:195] op_sel_hi:[1,0,1]
	v_pk_fma_f32 v[18:19], v[18:19], 0.5, v[196:197] op_sel_hi:[1,0,1]
	v_pk_fma_f32 v[12:13], v[12:13], 0.5, v[198:199] op_sel_hi:[1,0,1]
	v_pk_fma_f32 v[14:15], v[14:15], 0.5, v[200:201] op_sel_hi:[1,0,1]
	v_pk_fma_f32 v[8:9], v[8:9], 0.5, v[202:203] op_sel_hi:[1,0,1]
	v_pk_fma_f32 v[10:11], v[10:11], 0.5, v[204:205] op_sel_hi:[1,0,1]
	v_pk_fma_f32 v[4:5], v[4:5], 0.5, v[206:207] op_sel_hi:[1,0,1]
	v_pk_fma_f32 v[6:7], v[6:7], 0.5, v[208:209] op_sel_hi:[1,0,1]
	v_pk_fma_f32 v[0:1], v[0:1], 0.5, v[210:211] op_sel_hi:[1,0,1]
	v_pk_fma_f32 v[2:3], v[2:3], 0.5, v[212:213] op_sel_hi:[1,0,1]
	global_store_dwordx4 v218, v[28:31], s[88:89]
	global_store_dwordx4 v218, v[24:27], s[88:89] offset:512
	global_store_dwordx4 v219, v[20:23], s[88:89]
	global_store_dwordx4 v219, v[16:19], s[88:89] offset:512
	global_store_dwordx4 v220, v[12:15], s[88:89]
	global_store_dwordx4 v220, v[8:11], s[88:89] offset:512
	global_store_dwordx4 v221, v[4:7], s[88:89]
	global_store_dwordx4 v221, v[0:3], s[88:89] offset:512
	s_cbranch_vccnz .LBB0_721
	s_andn2_b64 vcc, exec, s[12:13]
	s_cbranch_vccnz .LBB0_720
	s_barrier
	s_branch .LBB0_720
